# mixer-even: item rotation keyed by XCD ((bx&7)%3) + XCD-aware item permutation (halo / v-row sharing in L2), on stack10
# speedup vs baseline: 1.0079x; 1.0079x over previous
; __device__ __forceinline__ void mixa_item(const Args& A, int li, int item, LAS unsigned char* lds, int tid, int lane, int wave) {
;     const int chunk = item >> 1, gh = item & 1, row0 = chunk * 128;
;     const bf16_t* UV = (const bf16_t*)(A.ws + WS_UV); bf16_t* CAT = (bf16_t*)(A.ws + WS_CAT);
;     const float* vg = A.in[8] + li * 512; const float* vb = A.in[9] + li * 512; const float* spb = A.in[7] + li * 8 * 128;
;     const bf16_t* spw = (const bf16_t*)(A.ws + WS_SPW) + (size_t)li * 8 * 128 * 128;
;     {
;         const int l15 = lane & 15, l4 = lane >> 4;
;         f32x4 gA[2][2], bA[2][2];
; #pragma unroll
;         for (int i = 0; i < 2; ++i) { const int chn = (l15 + 16 * (2 * gh + i)) * 8;
;             gA[i][0] = *(const f32x4*)(vg + chn); gA[i][1] = *(const f32x4*)(vg + chn + 4); bA[i][0] = *(const f32x4*)(vb + chn); bA[i][1] = *(const f32x4*)(vb + chn + 4); }
;         u32x4 w[4][4];
; #pragma unroll
;         for (int it = 0; it < 4; ++it)
; #pragma unroll
;             for (int i = 0; i < 4; ++i) w[it][i] = *(const u32x4*)(UV + (size_t)(row0 + wave * 16 + it * 4 + l4) * 1024 + 512 + (l15 + 16 * i) * 8);
;         u32x4 wsel[4][2];
; #pragma unroll
;         for (int it = 0; it < 4; ++it)
; #pragma unroll
;             for (int i = 0; i < 2; ++i) wsel[it][i] = *(const u32x4*)(UV + (size_t)(row0 + wave * 16 + it * 4 + l4) * 1024 + 512 + (l15 + 16 * (2 * gh + i)) * 8);
; #pragma unroll
;         for (int it = 0; it < 4; ++it) {
;             const int q = wave * 16 + it * 4 + l4; float s1 = 0.f, s2 = 0.f;
; #pragma unroll
;             for (int i = 0; i < 4; ++i)
; #pragma unroll
;                 for (int e = 0; e < 4; ++e) { const float a = bf_lo(w[it][i][e]), b = bf_hi(w[it][i][e]); s1 += a + b; s2 += a * a + b * b; }
;             s1 = sum16(s1); s2 = sum16(s2);
;             const float mean = s1 * (1.0f / 512.0f), rstd = __builtin_amdgcn_rsqf(fmaxf(s2 * (1.0f / 512.0f) - mean * mean, 0.f) + 1e-6f);
; #pragma unroll
;             for (int i = 0; i < 2; ++i) {
;                 const u32x4 ww = wsel[it][i]; u32x4 o;
; #pragma unroll
;                 for (int e = 0; e < 4; ++e) { const int h2 = e >> 1, k2 = (e & 1) * 2;
;                     const float a = (bf_lo(ww[e]) - mean) * rstd * gA[i][h2][k2] + bA[i][h2][k2], b = (bf_hi(ww[e]) - mean) * rstd * gA[i][h2][k2 + 1] + bA[i][h2][k2 + 1];
;                     o[e] = cvt_pk_bf16(a, b); }
.LBB0_433:
	s_and_b64 vcc, exec, s[0:1]
	s_cbranch_vccz .LBB0_480
	v_readlane_b32 s0, v252, 51
	v_readlane_b32 s1, v252, 52
	s_andn2_b64 vcc, exec, s[0:1]
	s_cbranch_vccnz .LBB0_480
	v_readlane_b32 s0, v254, 24
	v_readlane_b32 s1, v254, 25
	v_readlane_b32 s4, v254, 52
	v_readlane_b32 s68, v252, 31
	s_mov_b32 s3, s1
	s_lshl_b32 s2, s4, 9
	v_readlane_b32 s69, v252, 32
	s_lshl_b64 s[48:49], s[2:3], 2
	v_readlane_b32 s70, v252, 33
	v_readlane_b32 s71, v252, 34
	v_readlane_b32 s72, v252, 35
	v_readlane_b32 s73, v252, 36
	v_readlane_b32 s74, v252, 37
	v_readlane_b32 s75, v252, 38
	v_readlane_b32 s76, v252, 39
	v_readlane_b32 s77, v252, 40
	v_readlane_b32 s78, v252, 41
	v_readlane_b32 s79, v252, 42
	s_mov_b64 s[52:53], s[68:69]
	s_add_u32 s8, s52, s48
	v_readlane_b32 s80, v252, 43
	v_readlane_b32 s81, v252, 44
	v_readlane_b32 s82, v252, 45
	v_readlane_b32 s83, v252, 46
	s_mov_b64 s[54:55], s[70:71]
	s_addc_u32 s9, s53, s49
	s_mov_b64 s[56:57], s[72:73]
	s_mov_b64 s[58:59], s[74:75]
	s_mov_b64 s[60:61], s[76:77]
	s_mov_b64 s[62:63], s[78:79]
	s_add_u32 s16, s54, s48
	v_readlane_b32 s68, v252, 15
	s_addc_u32 s17, s55, s49
	s_lshl_b32 s2, s4, 10
	v_writelane_b32 v254, s0, 24
	v_readlane_b32 s82, v252, 29
	v_readlane_b32 s83, v252, 30
	v_writelane_b32 v254, s1, 25
	s_lshl_b64 s[0:1], s[2:3], 2
	s_mov_b64 s[22:23], s[82:83]
	s_add_u32 s26, s22, s0
	v_lshrrev_b32_e32 v6, 4, v168
	v_readlane_b32 s2, v254, 55
	s_addc_u32 s27, s23, s1
	s_movk_i32 s1, 0x2a0
	s_waitcnt vmcnt(0)
	v_lshl_or_b32 v113, s2, 4, v6
	s_lshl_b32 s0, s4, 18
	v_mul_lo_u32 v9, v113, s1
	v_readlane_b32 s1, v254, 0
	s_add_u32 s0, s1, s0
	v_readlane_b32 s1, v254, 1
	v_bfe_u32 v2, v160, 2, 2
	s_addc_u32 s1, s1, 0
	v_lshl_or_b32 v2, v6, 2, v2
	s_and_b32 s4, s5, 0xffffff80
	v_lshlrev_b32_e32 v3, 3, v168
	v_mul_u32_u24_e32 v2, 0x2a0, v2
	v_and_b32_e32 v3, 24, v3
	s_add_i32 s4, s4, 0
	v_add3_u32 v115, s4, v2, v3
	v_lshlrev_b32_e32 v2, 3, v6
	v_mov_b32_e32 v3, v177
	v_lshl_add_u64 v[4:5], s[0:1], 0, v[2:3]
	v_readlane_b32 s0, v253, 49
	s_movk_i32 s10, 0x980
	v_readlane_b32 s1, v253, 50
	v_cmp_gt_i32_e64 s[38:39], s10, v160
	s_movk_i32 s10, 0x780
	v_lshl_add_u64 v[116:117], s[0:1], 0, v[2:3]
	v_readlane_b32 s0, v254, 2
	v_cmp_gt_i32_e64 s[40:41], s10, v160
	s_movk_i32 s10, 0x580
	v_readlane_b32 s1, v254, 3
	v_cmp_gt_i32_e64 s[42:43], s10, v160
	s_movk_i32 s10, 0x380
	s_ashr_i32 s3, s5, 7
	v_lshl_add_u64 v[118:119], s[0:1], 0, v[2:3]
	v_lshlrev_b32_e32 v155, 4, v160
	v_readlane_b32 s0, v253, 53
	v_cmp_gt_i32_e64 s[44:45], s10, v160
	s_movk_i32 s10, 0x180
	v_and_b32_e32 v2, 0x3f0, v155
	v_readlane_b32 s1, v253, 54
	v_cmp_gt_i32_e64 s[46:47], s10, v160
	s_add_u32 s10, s58, s48
	v_and_b32_e32 v25, 0xff, v160
	v_lshl_add_u64 v[120:121], s[0:1], 0, v[2:3]
	s_addc_u32 s11, s59, s49
	v_lshlrev_b32_e32 v2, 3, v25
	v_lshl_add_u64 v[122:123], s[10:11], 0, v[2:3]
	s_lshl_b32 s11, s2, 2
	s_and_b32 s10, s11, -16
	s_add_i32 s14, 0, 0x10000
	v_ashrrev_i32_e32 v157, 6, v161
	v_lshlrev_b32_e32 v11, 4, v161
	s_add_u32 s20, s60, s48
	v_or_b32_e32 v161, s11, v6
	s_movk_i32 s11, 0x810
	s_waitcnt lgkmcnt(0)
	v_and_b32_e32 v1, 15, v160
	s_addc_u32 s21, s61, s49
	v_mul_lo_u32 v6, v161, s11
	v_lshlrev_b32_e32 v112, 3, v1
	v_lshlrev_b32_e32 v0, 4, v1
	s_waitcnt lgkmcnt(0)
	v_and_or_b32 v114, s5, 64, v1
	s_movk_i32 s4, 0xd80
	v_add_u32_e32 v26, s14, v6
	s_add_u32 s22, s62, s48
	v_lshlrev_b32_e32 v6, 2, v1
	v_mov_b32_e32 v1, v177
	s_movk_i32 s0, 0xf80
	v_cmp_gt_i32_e64 s[6:7], s4, v160
	s_movk_i32 s4, 0xb80
	s_addc_u32 s23, s63, s49
	v_lshl_add_u64 v[124:125], s[20:21], 0, v[0:1]
	s_lshr_b64 s[20:21], s[18:19], 1
	s_lshr_b32 s11, s19, 1
	v_ashrrev_i32_e32 v156, 6, v160
	v_cmp_gt_i32_e64 s[0:1], s0, v160
	v_cmp_gt_i32_e64 s[4:5], s4, v160
	v_add_u32_e32 v160, s14, v2
	s_mul_i32 s11, s11, 0xf800
	s_mul_hi_u32 s14, s20, 0xf800
	s_add_i32 s14, s14, s11
	s_mul_i32 s11, s20, 0xf800
	s_add_u32 s20, s56, s11
	s_addc_u32 s21, s57, s14
	s_lshl_b32 s2, s2, 12
	s_and_b32 s2, s2, 0xffffc000
	v_add_u32_e32 v7, 0, v0
	v_lshlrev_b32_e32 v13, 4, v162
	v_lshlrev_b32_e32 v15, 4, v163
	v_lshlrev_b32_e32 v17, 4, v164
	v_lshlrev_b32_e32 v19, 4, v165
	v_lshlrev_b32_e32 v21, 4, v166
	v_lshlrev_b32_e32 v24, 4, v167
	v_or_b32_e32 v8, 64, v6
	v_or_b32_e32 v10, 0x80, v6
	v_or_b32_e32 v12, 0xc0, v6
	v_or_b32_e32 v14, 0x100, v6
	v_or_b32_e32 v16, 0x140, v6
	v_or_b32_e32 v18, 0x180, v6
	v_or_b32_e32 v20, 0x1c0, v6
	v_lshlrev_b32_e32 v22, 8, v114
	v_mov_b32_e32 v23, v177
	s_add_i32 s2, s2, 0
	v_add_u32_e32 v148, 0x12600, v115
	v_add_u32_e32 v149, 0x12620, v115
	v_add_u32_e32 v150, 0x12640, v115
	v_add_u32_e32 v151, 0x12660, v115
	v_or_b32_e32 v152, 16, v114
	v_or_b32_e32 v153, 32, v114
	v_or_b32_e32 v154, 48, v114
	v_ashrrev_i32_e32 v158, 6, v162
	v_ashrrev_i32_e32 v159, 6, v163
	v_ashrrev_i32_e32 v168, 6, v164
	v_ashrrev_i32_e32 v169, 6, v165
	v_ashrrev_i32_e32 v170, 6, v166
	v_ashrrev_i32_e32 v171, 6, v167
	v_lshl_add_u64 v[126:127], s[22:23], 0, v[0:1]
	v_lshl_add_u64 v[128:129], v[4:5], 0, v[22:23]
	v_lshl_add_u64 v[130:131], s[20:21], 0, v[2:3]
	v_lshl_add_u32 v162, v25, 2, s2
	v_add_u32_e32 v163, v7, v9
	v_add_u32_e32 v164, 0, v11
	v_add_u32_e32 v165, 0, v13
	v_add_u32_e32 v166, 0, v15
	v_add_u32_e32 v167, 0, v17
	v_add_u32_e32 v172, 0, v19
	v_add_u32_e32 v173, 0, v21
	v_add_u32_e32 v174, 0, v24
	v_add_u32_e32 v175, v26, v0
	v_lshlrev_b32_e32 v132, 1, v6
	v_lshlrev_b32_e32 v134, 1, v8
	v_lshlrev_b32_e32 v136, 1, v10
	v_lshlrev_b32_e32 v138, 1, v12
	v_lshlrev_b32_e32 v140, 1, v14
	v_lshlrev_b32_e32 v142, 1, v16
	v_lshlrev_b32_e32 v144, 1, v18
	v_lshlrev_b32_e32 v146, 1, v20
	s_mov_b32 s2, s67
	s_mov_b32 s101, 0
	v_readlane_b32 s100, v252, 10
	s_cmp_lg_u32 s100, 0x100
	s_cbranch_scc1 .Lxr_plain
	s_and_b32 s100, s67, 7
	s_mul_i32 s101, s100, 11
	s_lshr_b32 s101, s101, 5
	s_mul_i32 s101, s101, 3
	s_sub_i32 s100, s100, s101
	s_lshl_b32 s100, s100, 8
	s_add_i32 s2, s67, s100
	s_mov_b32 s101, 3

; __device__ __forceinline__ float bf_lo(unsigned w) { return __uint_as_float(w << 16); }
; __device__ __forceinline__ float bf_hi(unsigned w) { return __uint_as_float(w & 0xffff0000u); }
; __device__ __forceinline__ void mixa_item(const Args& A, int li, int item, LAS unsigned char* lds, int tid, int lane, int wave) {
;     const int chunk = item >> 1, gh = item & 1, row0 = chunk * 128;
;     const bf16_t* UV = (const bf16_t*)(A.ws + WS_UV); bf16_t* CAT = (bf16_t*)(A.ws + WS_CAT);
;     const float* vg = A.in[8] + li * 512; const float* vb = A.in[9] + li * 512; const float* spb = A.in[7] + li * 8 * 128;
;     const bf16_t* spw = (const bf16_t*)(A.ws + WS_SPW) + (size_t)li * 8 * 128 * 128;
;     {
;         const int l15 = lane & 15, l4 = lane >> 4;
;         f32x4 gA[2][2], bA[2][2];
; #pragma unroll
;         for (int i = 0; i < 2; ++i) { const int chn = (l15 + 16 * (2 * gh + i)) * 8;
;             gA[i][0] = *(const f32x4*)(vg + chn); gA[i][1] = *(const f32x4*)(vg + chn + 4); bA[i][0] = *(const f32x4*)(vb + chn); bA[i][1] = *(const f32x4*)(vb + chn + 4); }
;         u32x4 w[4][4];
; #pragma unroll
;         for (int it = 0; it < 4; ++it)
; #pragma unroll
;             for (int i = 0; i < 4; ++i) w[it][i] = *(const u32x4*)(UV + (size_t)(row0 + wave * 16 + it * 4 + l4) * 1024 + 512 + (l15 + 16 * i) * 8);
;         u32x4 wsel[4][2];
; #pragma unroll
;         for (int it = 0; it < 4; ++it)
; #pragma unroll
;             for (int i = 0; i < 2; ++i) wsel[it][i] = *(const u32x4*)(UV + (size_t)(row0 + wave * 16 + it * 4 + l4) * 1024 + 512 + (l15 + 16 * (2 * gh + i)) * 8);
; #pragma unroll
;         for (int it = 0; it < 4; ++it) {
;             const int q = wave * 16 + it * 4 + l4; float s1 = 0.f, s2 = 0.f;
; #pragma unroll
;             for (int i = 0; i < 4; ++i)
; #pragma unroll
;                 for (int e = 0; e < 4; ++e) { const float a = bf_lo(w[it][i][e]), b = bf_hi(w[it][i][e]); s1 += a + b; s2 += a * a + b * b; }
;             s1 = sum16(s1); s2 = sum16(s2);
;             const float mean = s1 * (1.0f / 512.0f), rstd = __builtin_amdgcn_rsqf(fmaxf(s2 * (1.0f / 512.0f) - mean * mean, 0.f) + 1e-6f);
.LBB0_438:
	s_cmpk_gt_i32 s2, 0xff
	s_cbranch_scc1 .LBB0_440
	s_and_b32 s100, s2, 7
	s_lshl_b32 s100, s100, 5
	s_bfe_u32 s11, s2, 0x50003
	s_or_b32 s100, s100, s11
	s_lshl_b32 s11, s100, 6
	s_and_b32 s11, s11, 0xffffff80
	v_add_u32_e32 v32, s11, v113
	v_ashrrev_i32_e32 v33, 31, v32
	v_readlane_b32 s12, v253, 49
	v_lshlrev_b64 v[0:1], 11, v[32:33]
	v_readlane_b32 s13, v253, 50
	v_lshlrev_b32_e32 v36, 1, v112
	v_mov_b32_e32 v37, v177
	v_lshl_add_u64 v[34:35], s[12:13], 0, v[0:1]
	v_lshl_add_u64 v[38:39], v[34:35], 0, v[36:37]
	global_load_dwordx4 v[40:43], v[38:39], off offset:1024
	global_load_dwordx4 v[48:51], v[38:39], off offset:1280
	global_load_dwordx4 v[194:197], v[38:39], off offset:1536
	s_and_b32 s14, s100, 1
	v_lshl_or_b32 v0, s14, 8, v112
	v_lshlrev_b32_e32 v12, 2, v0
	v_lshlrev_b32_e32 v44, 1, v0
	global_load_dwordx4 v[16:19], v12, s[8:9] offset:16
	global_load_dwordx4 v[24:27], v12, s[8:9]
	global_load_dwordx4 v[20:23], v12, s[16:17] offset:16
	global_load_dwordx4 v[28:31], v12, s[16:17]
	global_load_dwordx4 v[0:3], v12, s[8:9] offset:528
	global_load_dwordx4 v[8:11], v12, s[8:9] offset:512
	global_load_dwordx4 v[4:7], v12, s[16:17] offset:528
	s_nop 0
	global_load_dwordx4 v[12:15], v12, s[16:17] offset:512
	v_mov_b32_e32 v45, v177
	global_load_dwordx4 v[198:201], v[38:39], off offset:1792
	v_lshl_add_u64 v[34:35], v[34:35], 0, v[44:45]
	global_load_dwordx4 v[108:111], v[34:35], off offset:1024
	global_load_dwordx4 v[104:107], v[34:35], off offset:1280
	v_or_b32_e32 v46, 4, v32
	v_or_b32_e32 v52, 8, v32
	v_or_b32_e32 v32, 12, v32
	v_ashrrev_i32_e32 v47, 31, v46
	v_ashrrev_i32_e32 v53, 31, v52
	v_ashrrev_i32_e32 v33, 31, v32
	v_lshlrev_b64 v[46:47], 11, v[46:47]
	v_lshlrev_b64 v[52:53], 11, v[52:53]
	v_lshlrev_b64 v[32:33], 11, v[32:33]
	v_lshl_add_u64 v[46:47], s[12:13], 0, v[46:47]
	v_lshl_add_u64 v[52:53], s[12:13], 0, v[52:53]
	v_lshl_add_u64 v[32:33], s[12:13], 0, v[32:33]
	v_lshl_add_u64 v[38:39], v[46:47], 0, v[36:37]
	v_lshl_add_u64 v[54:55], v[52:53], 0, v[36:37]
	v_lshl_add_u64 v[56:57], v[32:33], 0, v[36:37]
	v_lshl_add_u64 v[58:59], v[46:47], 0, v[44:45]
	v_lshl_add_u64 v[178:179], v[52:53], 0, v[44:45]
	v_lshl_add_u64 v[202:203], v[32:33], 0, v[44:45]
	global_load_dwordx4 v[100:103], v[38:39], off offset:1024
	global_load_dwordx4 v[96:99], v[38:39], off offset:1280
	global_load_dwordx4 v[92:95], v[38:39], off offset:1536
	global_load_dwordx4 v[88:91], v[38:39], off offset:1792
	global_load_dwordx4 v[76:79], v[54:55], off offset:1024
	global_load_dwordx4 v[72:75], v[54:55], off offset:1280
	global_load_dwordx4 v[68:71], v[54:55], off offset:1536
	global_load_dwordx4 v[64:67], v[54:55], off offset:1792
	s_nop 0
	global_load_dwordx4 v[52:55], v[56:57], off offset:1024
	global_load_dwordx4 v[44:47], v[56:57], off offset:1280
	global_load_dwordx4 v[36:39], v[56:57], off offset:1536
	global_load_dwordx4 v[32:35], v[56:57], off offset:1792
	global_load_dwordx4 v[84:87], v[58:59], off offset:1024
	global_load_dwordx4 v[80:83], v[58:59], off offset:1280
	global_load_dwordx4 v[60:63], v[178:179], off offset:1024
	s_nop 0
	global_load_dwordx4 v[56:59], v[178:179], off offset:1280
	s_movk_i32 s13, 0xffdf
	s_mov_b32 s12, 0x3b000000
	s_lshl_b32 s14, s14, 2
	s_add_i32 s48, s14, s3
	s_ashr_i32 s49, s48, 31
	s_lshl_b64 s[20:21], s[48:49], 15
	s_movk_i32 s14, 0x1000
	s_waitcnt vmcnt(29)
	v_lshlrev_b32_e32 v179, 16, v40
	v_lshlrev_b32_e32 v178, 16, v41
	v_and_b32_e32 v133, 0xffff0000, v40
	v_pk_mul_f32 v[228:229], v[178:179], v[178:179]
	v_and_b32_e32 v41, 0xffff0000, v41
	v_pk_mov_b32 v[228:229], v[228:229], v[178:179] op_sel:[1,0]
	v_mul_f32_e32 v40, v133, v133
	s_waitcnt vmcnt(28)
	v_lshlrev_b32_e32 v217, 16, v50
	v_and_b32_e32 v219, 0xffff0000, v50
	v_mul_f32_e32 v50, v41, v41
	v_pk_add_f32 v[40:41], v[228:229], v[40:41]
	v_mul_f32_e32 v228, v178, v178
	v_pk_add_f32 v[178:179], v[178:179], v[132:133]
	v_lshlrev_b32_e32 v205, 16, v42
	v_and_b32_e32 v207, 0xffff0000, v42
	v_lshlrev_b32_e32 v221, 16, v51
	v_and_b32_e32 v223, 0xffff0000, v51
	v_mov_b32_e32 v229, v179
	v_mov_b32_e32 v51, v177
	v_lshlrev_b32_e32 v209, 16, v43
	v_and_b32_e32 v43, 0xffff0000, v43
	v_mul_f32_e32 v204, v205, v205
	v_mul_f32_e32 v206, v207, v207
	v_pk_add_f32 v[50:51], v[228:229], v[50:51]
	v_lshlrev_b32_e32 v211, 16, v48
	v_and_b32_e32 v213, 0xffff0000, v48
	v_mul_f32_e32 v208, v209, v209
	v_mul_f32_e32 v42, v43, v43
	v_pk_add_f32 v[40:41], v[40:41], v[50:51]
	v_pk_add_f32 v[50:51], v[204:205], v[206:207]
	v_lshlrev_b32_e32 v215, 16, v49
	v_and_b32_e32 v49, 0xffff0000, v49
	v_mul_f32_e32 v210, v211, v211
	v_mul_f32_e32 v212, v213, v213
	v_pk_add_f32 v[40:41], v[50:51], v[40:41]
	v_pk_add_f32 v[42:43], v[208:209], v[42:43]
	v_mul_f32_e32 v214, v215, v215
	v_mul_f32_e32 v48, v49, v49
	v_pk_add_f32 v[40:41], v[42:43], v[40:41]
	v_pk_add_f32 v[42:43], v[210:211], v[212:213]
	v_mul_f32_e32 v216, v217, v217
	v_mul_f32_e32 v218, v219, v219
	v_pk_add_f32 v[40:41], v[42:43], v[40:41]
	v_pk_add_f32 v[42:43], v[214:215], v[48:49]
	v_mul_f32_e32 v220, v221, v221
	v_mul_f32_e32 v222, v223, v223
	s_waitcnt vmcnt(27)
	v_lshlrev_b32_e32 v225, 16, v194
	v_and_b32_e32 v227, 0xffff0000, v194
	v_pk_add_f32 v[40:41], v[42:43], v[40:41]
	v_pk_add_f32 v[42:43], v[216:217], v[218:219]
	v_mul_f32_e32 v224, v225, v225
	v_mul_f32_e32 v226, v227, v227
	v_pk_add_f32 v[40:41], v[42:43], v[40:41]
	v_pk_add_f32 v[42:43], v[220:221], v[222:223]
	v_and_b32_e32 v49, 0xffff0000, v195
	v_pk_add_f32 v[40:41], v[42:43], v[40:41]
	v_pk_add_f32 v[42:43], v[224:225], v[226:227]
	v_mul_f32_e32 v48, v49, v49
	v_pk_add_f32 v[40:41], v[42:43], v[40:41]
	v_lshlrev_b32_e32 v43, 16, v195
	v_mul_f32_e32 v42, v43, v43
	v_pk_add_f32 v[42:43], v[42:43], v[48:49]
	v_lshlrev_b32_e32 v49, 16, v196
	v_and_b32_e32 v51, 0xffff0000, v196
	v_mul_f32_e32 v48, v49, v49
	v_mul_f32_e32 v50, v51, v51
	v_lshlrev_b32_e32 v179, 16, v197
	v_and_b32_e32 v195, 0xffff0000, v197
	v_mul_f32_e32 v178, v179, v179
	v_mul_f32_e32 v194, v195, v195
	s_waitcnt vmcnt(18)
; __device__ __forceinline__ unsigned cvt_pk_bf16(float lo, float hi) { unsigned r; asm volatile("v_cvt_pk_bf16_f32 %0, %1, %2" : "=v"(r) : "v"(lo), "v"(hi)); return r; }
; #define LAS __attribute__((address_space(3)))
; __device__ __forceinline__ float bf_lo(unsigned w) { return __uint_as_float(w << 16); }
; __device__ __forceinline__ float bf_hi(unsigned w) { return __uint_as_float(w & 0xffff0000u); }
; __device__ __forceinline__ void mixa_item(const Args& A, int li, int item, LAS unsigned char* lds, int tid, int lane, int wave) {
;     ...
;         for (int it = 0; it < 4; ++it) {
;             const int q = wave * 16 + it * 4 + l4; float s1 = 0.f, s2 = 0.f;
; #pragma unroll
;             for (int i = 0; i < 4; ++i)
; #pragma unroll
;                 for (int e = 0; e < 4; ++e) { const float a = bf_lo(w[it][i][e]), b = bf_hi(w[it][i][e]); s1 += a + b; s2 += a * a + b * b; }
;             s1 = sum16(s1); s2 = sum16(s2);
;             const float mean = s1 * (1.0f / 512.0f), rstd = __builtin_amdgcn_rsqf(fmaxf(s2 * (1.0f / 512.0f) - mean * mean, 0.f) + 1e-6f);
; #pragma unroll
;             for (int i = 0; i < 2; ++i) {
;                 const u32x4 ww = wsel[it][i]; u32x4 o;
; #pragma unroll
;                 for (int e = 0; e < 4; ++e) { const int h2 = e >> 1, k2 = (e & 1) * 2;
;                     const float a = (bf_lo(ww[e]) - mean) * rstd * gA[i][h2][k2] + bA[i][h2][k2], b = (bf_hi(ww[e]) - mean) * rstd * gA[i][h2][k2 + 1] + bA[i][h2][k2 + 1];
;                     o[e] = cvt_pk_bf16(a, b); }
;                 *(LAS u32x4*)(lds + q * VN_STRIDE + (l15 + 16 * i) * 16) = o;
;             }
	v_lshlrev_b32_e32 v197, 16, v198
	v_and_b32_e32 v205, 0xffff0000, v198
	v_pk_add_f32 v[40:41], v[42:43], v[40:41]
	v_pk_add_f32 v[42:43], v[48:49], v[50:51]
	v_mul_f32_e32 v196, v197, v197
	v_mul_f32_e32 v204, v205, v205
	v_lshlrev_b32_e32 v207, 16, v199
	v_and_b32_e32 v199, 0xffff0000, v199
	v_pk_add_f32 v[40:41], v[42:43], v[40:41]
	v_pk_add_f32 v[42:43], v[178:179], v[194:195]
	v_mul_f32_e32 v206, v207, v207
	v_mul_f32_e32 v198, v199, v199
	v_lshlrev_b32_e32 v209, 16, v200
	v_and_b32_e32 v211, 0xffff0000, v200
	v_pk_add_f32 v[40:41], v[42:43], v[40:41]
	v_pk_add_f32 v[42:43], v[196:197], v[204:205]
	v_mul_f32_e32 v208, v209, v209
	v_mul_f32_e32 v210, v211, v211
	v_lshlrev_b32_e32 v213, 16, v201
	v_and_b32_e32 v201, 0xffff0000, v201
	v_pk_add_f32 v[40:41], v[42:43], v[40:41]
	v_pk_add_f32 v[42:43], v[206:207], v[198:199]
	v_mul_f32_e32 v212, v213, v213
	v_mul_f32_e32 v200, v201, v201
	v_pk_add_f32 v[40:41], v[42:43], v[40:41]
	v_pk_add_f32 v[42:43], v[208:209], v[210:211]
	s_waitcnt vmcnt(17)
	v_lshlrev_b32_e32 v135, 16, v108
	v_pk_add_f32 v[40:41], v[42:43], v[40:41]
	v_pk_add_f32 v[42:43], v[212:213], v[200:201]
	v_and_b32_e32 v108, 0xffff0000, v108
	v_pk_add_f32 v[40:41], v[42:43], v[40:41]
	s_waitcnt vmcnt(15)
	v_and_b32_e32 v195, 0xffff0000, v102
	v_mul_f32_e32 v194, v195, v195
	v_mov_b32_dpp v43, v41 quad_perm:[1,0,3,2] row_mask:0xf bank_mask:0xf bound_ctrl:1
	v_mov_b32_dpp v42, v40 quad_perm:[1,0,3,2] row_mask:0xf bank_mask:0xf bound_ctrl:1
	v_pk_add_f32 v[40:41], v[40:41], v[42:43]
	v_lshlrev_b32_e32 v197, 16, v103
	v_and_b32_e32 v103, 0xffff0000, v103
	v_mov_b32_dpp v43, v41 quad_perm:[2,3,0,1] row_mask:0xf bank_mask:0xf bound_ctrl:1
	v_mov_b32_dpp v42, v40 quad_perm:[2,3,0,1] row_mask:0xf bank_mask:0xf bound_ctrl:1
	v_pk_add_f32 v[40:41], v[40:41], v[42:43]
	v_mul_f32_e32 v196, v197, v197
	s_waitcnt vmcnt(14)
	v_lshlrev_b32_e32 v199, 16, v96
	v_mov_b32_dpp v43, v41 row_half_mirror row_mask:0xf bank_mask:0xf bound_ctrl:1
	v_mov_b32_dpp v42, v40 row_half_mirror row_mask:0xf bank_mask:0xf bound_ctrl:1
	v_pk_add_f32 v[40:41], v[40:41], v[42:43]
	v_and_b32_e32 v201, 0xffff0000, v96
	v_mul_f32_e32 v198, v199, v199
	v_mov_b32_dpp v43, v41 row_mirror row_mask:0xf bank_mask:0xf bound_ctrl:1
	v_mov_b32_dpp v42, v40 row_mirror row_mask:0xf bank_mask:0xf bound_ctrl:1
	v_pk_add_f32 v[40:41], v[40:41], v[42:43]
	v_mul_f32_e32 v200, v201, v201
	v_pk_mul_f32 v[178:179], v[40:41], s[12:13] op_sel_hi:[1,0]
	v_lshlrev_b32_e32 v205, 16, v98
	v_fma_f32 v40, -v179, v179, v178
	v_max_f32_e32 v40, 0, v40
	v_add_f32_e32 v40, 0x358637bd, v40
	v_rsq_f32_e32 v133, v40
	v_sub_f32_e32 v135, v135, v179
	v_sub_f32_e32 v108, v108, v179
	global_load_dwordx4 v[48:51], v[202:203], off offset:1024
	global_load_dwordx4 v[40:43], v[202:203], off offset:1280
	v_mul_f32_e32 v135, v135, v133
	v_mul_f32_e32 v108, v108, v133
	v_fma_f32 v135, v24, v135, v28
	v_fma_f32 v108, v25, v108, v29
	v_cvt_pk_bf16_f32 v108, v135, v108
	v_lshlrev_b32_e32 v135, 16, v109
	v_and_b32_e32 v109, 0xffff0000, v109
	v_sub_f32_e32 v135, v135, v179
	v_sub_f32_e32 v109, v109, v179
	v_mul_f32_e32 v135, v135, v133
	v_mul_f32_e32 v109, v109, v133
	v_fma_f32 v135, v26, v135, v30
	v_fma_f32 v109, v27, v109, v31
	v_cvt_pk_bf16_f32 v109, v135, v109
	v_lshlrev_b32_e32 v135, 16, v110
	v_and_b32_e32 v110, 0xffff0000, v110
	v_sub_f32_e32 v135, v135, v179
	v_sub_f32_e32 v110, v110, v179
	v_mul_f32_e32 v135, v135, v133
	v_mul_f32_e32 v110, v110, v133
	v_fma_f32 v135, v16, v135, v20
	v_fma_f32 v110, v17, v110, v21
	v_cvt_pk_bf16_f32 v110, v135, v110
	v_lshlrev_b32_e32 v135, 16, v111
	v_and_b32_e32 v111, 0xffff0000, v111
	v_sub_f32_e32 v111, v111, v179
	v_sub_f32_e32 v135, v135, v179
	v_mul_f32_e32 v111, v111, v133
	v_mul_f32_e32 v135, v135, v133
	v_fma_f32 v111, v19, v111, v23
	v_fma_f32 v135, v18, v135, v22
	v_cvt_pk_bf16_f32 v111, v135, v111
	ds_write_b128 v163, v[108:111]
	v_lshlrev_b32_e32 v108, 16, v104
	v_and_b32_e32 v104, 0xffff0000, v104
	v_sub_f32_e32 v108, v108, v179
	v_sub_f32_e32 v104, v104, v179
	v_mul_f32_e32 v108, v108, v133
	v_mul_f32_e32 v104, v104, v133
	v_fma_f32 v108, v8, v108, v12
	v_fma_f32 v104, v9, v104, v13
	v_cvt_pk_bf16_f32 v104, v108, v104
	v_lshlrev_b32_e32 v108, 16, v105
	v_and_b32_e32 v105, 0xffff0000, v105
	v_sub_f32_e32 v108, v108, v179
	v_sub_f32_e32 v105, v105, v179
	v_mul_f32_e32 v108, v108, v133
	v_mul_f32_e32 v105, v105, v133
	v_fma_f32 v108, v10, v108, v14
	v_fma_f32 v105, v11, v105, v15
	v_cvt_pk_bf16_f32 v105, v108, v105
	v_lshlrev_b32_e32 v108, 16, v106
	v_and_b32_e32 v106, 0xffff0000, v106
	v_sub_f32_e32 v108, v108, v179
	v_sub_f32_e32 v106, v106, v179
	v_mul_f32_e32 v108, v108, v133
	v_mul_f32_e32 v106, v106, v133
	v_fma_f32 v108, v0, v108, v4
	v_fma_f32 v106, v1, v106, v5
	v_cvt_pk_bf16_f32 v106, v108, v106
	v_lshlrev_b32_e32 v108, 16, v107
	v_and_b32_e32 v107, 0xffff0000, v107
	v_sub_f32_e32 v108, v108, v179
	v_sub_f32_e32 v107, v107, v179
	v_mul_f32_e32 v108, v108, v133
	v_mul_f32_e32 v107, v107, v133
	v_fma_f32 v108, v2, v108, v6
	v_fma_f32 v107, v3, v107, v7
	v_cvt_pk_bf16_f32 v107, v108, v107
	v_lshlrev_b32_e32 v109, 16, v100
	v_lshlrev_b32_e32 v108, 16, v101
	v_and_b32_e32 v111, 0xffff0000, v100
	v_and_b32_e32 v101, 0xffff0000, v101
	v_pk_mul_f32 v[214:215], v[108:109], v[108:109]
	v_mul_f32_e32 v110, v101, v101
	v_pk_mov_b32 v[214:215], v[214:215], v[108:109] op_sel:[1,0]
	v_mul_f32_e32 v100, v111, v111
	v_pk_add_f32 v[100:101], v[214:215], v[100:101]
	v_mul_f32_e32 v214, v108, v108
	v_pk_add_f32 v[108:109], v[108:109], v[110:111]
	v_lshlrev_b32_e32 v179, 16, v102
	v_mov_b32_e32 v215, v109
	v_mov_b32_e32 v111, v177
	v_mul_f32_e32 v178, v179, v179
	v_pk_add_f32 v[108:109], v[214:215], v[110:111]
	v_mul_f32_e32 v102, v103, v103
	v_pk_add_f32 v[100:101], v[100:101], v[108:109]
	v_pk_add_f32 v[108:109], v[178:179], v[194:195]
	v_lshlrev_b32_e32 v203, 16, v97
	v_and_b32_e32 v97, 0xffff0000, v97
	v_pk_add_f32 v[100:101], v[108:109], v[100:101]
	v_pk_add_f32 v[102:103], v[196:197], v[102:103]
	v_mul_f32_e32 v202, v203, v203
	v_mul_f32_e32 v96, v97, v97
	v_and_b32_e32 v207, 0xffff0000, v98
	v_pk_add_f32 v[100:101], v[102:103], v[100:101]
	v_pk_add_f32 v[102:103], v[198:199], v[200:201]
	v_mul_f32_e32 v204, v205, v205
	v_mul_f32_e32 v206, v207, v207
	v_lshlrev_b32_e32 v209, 16, v99
	v_and_b32_e32 v99, 0xffff0000, v99
	v_pk_add_f32 v[100:101], v[102:103], v[100:101]
	v_pk_add_f32 v[96:97], v[202:203], v[96:97]
	v_mul_f32_e32 v208, v209, v209
	v_mul_f32_e32 v98, v99, v99
	s_waitcnt vmcnt(15)
; __device__ __forceinline__ unsigned cvt_pk_bf16(float lo, float hi) { unsigned r; asm volatile("v_cvt_pk_bf16_f32 %0, %1, %2" : "=v"(r) : "v"(lo), "v"(hi)); return r; }
; #define LAS __attribute__((address_space(3)))
; __device__ __forceinline__ float bf_lo(unsigned w) { return __uint_as_float(w << 16); }
; __device__ __forceinline__ float bf_hi(unsigned w) { return __uint_as_float(w & 0xffff0000u); }
; __device__ __forceinline__ void mixa_item(const Args& A, int li, int item, LAS unsigned char* lds, int tid, int lane, int wave) {
;     ...
;         for (int it = 0; it < 4; ++it) {
;             const int q = wave * 16 + it * 4 + l4; float s1 = 0.f, s2 = 0.f;
; #pragma unroll
;             for (int i = 0; i < 4; ++i)
; #pragma unroll
;                 for (int e = 0; e < 4; ++e) { const float a = bf_lo(w[it][i][e]), b = bf_hi(w[it][i][e]); s1 += a + b; s2 += a * a + b * b; }
;             s1 = sum16(s1); s2 = sum16(s2);
;             const float mean = s1 * (1.0f / 512.0f), rstd = __builtin_amdgcn_rsqf(fmaxf(s2 * (1.0f / 512.0f) - mean * mean, 0.f) + 1e-6f);
; #pragma unroll
;             for (int i = 0; i < 2; ++i) {
;                 const u32x4 ww = wsel[it][i]; u32x4 o;
; #pragma unroll
;                 for (int e = 0; e < 4; ++e) { const int h2 = e >> 1, k2 = (e & 1) * 2;
;                     const float a = (bf_lo(ww[e]) - mean) * rstd * gA[i][h2][k2] + bA[i][h2][k2], b = (bf_hi(ww[e]) - mean) * rstd * gA[i][h2][k2 + 1] + bA[i][h2][k2 + 1];
;                     o[e] = cvt_pk_bf16(a, b); }
;                 *(LAS u32x4*)(lds + q * VN_STRIDE + (l15 + 16 * i) * 16) = o;
;             }
	v_lshlrev_b32_e32 v211, 16, v92
	v_and_b32_e32 v213, 0xffff0000, v92
	v_pk_add_f32 v[96:97], v[96:97], v[100:101]
	v_pk_add_f32 v[100:101], v[204:205], v[206:207]
	v_mul_f32_e32 v210, v211, v211
	v_mul_f32_e32 v212, v213, v213
	v_pk_add_f32 v[96:97], v[100:101], v[96:97]
	v_pk_add_f32 v[98:99], v[208:209], v[98:99]
	v_and_b32_e32 v101, 0xffff0000, v94
	v_pk_add_f32 v[96:97], v[98:99], v[96:97]
	v_pk_add_f32 v[98:99], v[210:211], v[212:213]
	v_mul_f32_e32 v100, v101, v101
	v_pk_add_f32 v[96:97], v[98:99], v[96:97]
	v_lshlrev_b32_e32 v99, 16, v93
	v_and_b32_e32 v93, 0xffff0000, v93
	v_mul_f32_e32 v98, v99, v99
	v_mul_f32_e32 v92, v93, v93
	v_pk_add_f32 v[92:93], v[98:99], v[92:93]
	v_lshlrev_b32_e32 v99, 16, v94
	v_mul_f32_e32 v98, v99, v99
	v_lshlrev_b32_e32 v103, 16, v95
	v_and_b32_e32 v95, 0xffff0000, v95
	v_mul_f32_e32 v102, v103, v103
	v_mul_f32_e32 v94, v95, v95
	s_waitcnt vmcnt(14)
	v_lshlrev_b32_e32 v109, 16, v88
	v_and_b32_e32 v111, 0xffff0000, v88
	v_pk_add_f32 v[92:93], v[92:93], v[96:97]
	v_pk_add_f32 v[96:97], v[98:99], v[100:101]
	v_mul_f32_e32 v108, v109, v109
	v_mul_f32_e32 v110, v111, v111
	v_lshlrev_b32_e32 v179, 16, v89
	v_and_b32_e32 v89, 0xffff0000, v89
	v_pk_add_f32 v[92:93], v[96:97], v[92:93]
	v_pk_add_f32 v[94:95], v[102:103], v[94:95]
	v_mul_f32_e32 v178, v179, v179
	v_mul_f32_e32 v88, v89, v89
	v_lshlrev_b32_e32 v195, 16, v90
	v_and_b32_e32 v197, 0xffff0000, v90
	v_pk_add_f32 v[92:93], v[94:95], v[92:93]
	v_pk_add_f32 v[94:95], v[108:109], v[110:111]
	v_mul_f32_e32 v194, v195, v195
	v_mul_f32_e32 v196, v197, v197
	v_lshlrev_b32_e32 v199, 16, v91
	v_and_b32_e32 v91, 0xffff0000, v91
	v_pk_add_f32 v[92:93], v[94:95], v[92:93]
	v_pk_add_f32 v[88:89], v[178:179], v[88:89]
	v_mul_f32_e32 v198, v199, v199
	v_mul_f32_e32 v90, v91, v91
	v_pk_add_f32 v[88:89], v[88:89], v[92:93]
	v_pk_add_f32 v[92:93], v[194:195], v[196:197]
	v_pk_add_f32 v[90:91], v[198:199], v[90:91]
	v_pk_add_f32 v[88:89], v[92:93], v[88:89]
	ds_write_b128 v163, v[104:107] offset:256
	v_pk_add_f32 v[88:89], v[90:91], v[88:89]
	s_waitcnt vmcnt(13)
	v_lshlrev_b32_e32 v93, 16, v79
	v_and_b32_e32 v79, 0xffff0000, v79
	v_mov_b32_dpp v91, v89 quad_perm:[1,0,3,2] row_mask:0xf bank_mask:0xf bound_ctrl:1
	v_mov_b32_dpp v90, v88 quad_perm:[1,0,3,2] row_mask:0xf bank_mask:0xf bound_ctrl:1
	v_pk_add_f32 v[88:89], v[88:89], v[90:91]
	v_mul_f32_e32 v92, v93, v93
	s_waitcnt vmcnt(12)
	v_lshlrev_b32_e32 v95, 16, v72
	v_mov_b32_dpp v91, v89 quad_perm:[2,3,0,1] row_mask:0xf bank_mask:0xf bound_ctrl:1
	v_mov_b32_dpp v90, v88 quad_perm:[2,3,0,1] row_mask:0xf bank_mask:0xf bound_ctrl:1
	v_pk_add_f32 v[88:89], v[88:89], v[90:91]
	v_and_b32_e32 v97, 0xffff0000, v72
	v_mul_f32_e32 v94, v95, v95
	v_mov_b32_dpp v91, v89 row_half_mirror row_mask:0xf bank_mask:0xf bound_ctrl:1
	v_mov_b32_dpp v90, v88 row_half_mirror row_mask:0xf bank_mask:0xf bound_ctrl:1
	v_pk_add_f32 v[88:89], v[88:89], v[90:91]
	v_mul_f32_e32 v96, v97, v97
	v_lshlrev_b32_e32 v99, 16, v73
	v_mov_b32_dpp v91, v89 row_mirror row_mask:0xf bank_mask:0xf bound_ctrl:1
	v_mov_b32_dpp v90, v88 row_mirror row_mask:0xf bank_mask:0xf bound_ctrl:1
	v_pk_add_f32 v[88:89], v[88:89], v[90:91]
	s_waitcnt vmcnt(5)
	v_lshlrev_b32_e32 v90, 16, v84
	v_pk_mul_f32 v[88:89], v[88:89], s[12:13] op_sel_hi:[1,0]
	v_and_b32_e32 v84, 0xffff0000, v84
	v_fma_f32 v88, -v89, v89, v88
	v_max_f32_e32 v88, 0, v88
	v_add_f32_e32 v88, 0x358637bd, v88
	v_rsq_f32_e32 v88, v88
	v_sub_f32_e32 v90, v90, v89
	v_sub_f32_e32 v84, v84, v89
	v_and_b32_e32 v91, 0xffff0000, v78
	v_mul_f32_e32 v90, v90, v88
	v_mul_f32_e32 v84, v84, v88
	v_fma_f32 v90, v24, v90, v28
	v_fma_f32 v84, v25, v84, v29
	v_cvt_pk_bf16_f32 v84, v90, v84
	v_lshlrev_b32_e32 v90, 16, v85
	v_and_b32_e32 v85, 0xffff0000, v85
	v_sub_f32_e32 v90, v90, v89
	v_sub_f32_e32 v85, v85, v89
	v_mul_f32_e32 v90, v90, v88
	v_mul_f32_e32 v85, v85, v88
	v_fma_f32 v90, v26, v90, v30
	v_fma_f32 v85, v27, v85, v31
	v_cvt_pk_bf16_f32 v85, v90, v85
	v_lshlrev_b32_e32 v90, 16, v86
	v_and_b32_e32 v86, 0xffff0000, v86
	v_sub_f32_e32 v90, v90, v89
	v_sub_f32_e32 v86, v86, v89
	v_mul_f32_e32 v90, v90, v88
	v_mul_f32_e32 v86, v86, v88
	v_fma_f32 v90, v16, v90, v20
	v_fma_f32 v86, v17, v86, v21
	v_cvt_pk_bf16_f32 v86, v90, v86
	v_lshlrev_b32_e32 v90, 16, v87
	v_and_b32_e32 v87, 0xffff0000, v87
	v_sub_f32_e32 v87, v87, v89
	v_sub_f32_e32 v90, v90, v89
	v_mul_f32_e32 v87, v87, v88
	v_mul_f32_e32 v90, v90, v88
	v_fma_f32 v87, v19, v87, v23
	v_fma_f32 v90, v18, v90, v22
	v_cvt_pk_bf16_f32 v87, v90, v87
	ds_write_b128 v163, v[84:87] offset:2688
	s_waitcnt vmcnt(4)
; __device__ __forceinline__ unsigned cvt_pk_bf16(float lo, float hi) { unsigned r; asm volatile("v_cvt_pk_bf16_f32 %0, %1, %2" : "=v"(r) : "v"(lo), "v"(hi)); return r; }
; #define LAS __attribute__((address_space(3)))
; __device__ __forceinline__ float bf_lo(unsigned w) { return __uint_as_float(w << 16); }
; __device__ __forceinline__ float bf_hi(unsigned w) { return __uint_as_float(w & 0xffff0000u); }
; __device__ __forceinline__ void mixa_item(const Args& A, int li, int item, LAS unsigned char* lds, int tid, int lane, int wave) {
;     ...
;         for (int it = 0; it < 4; ++it) {
;             const int q = wave * 16 + it * 4 + l4; float s1 = 0.f, s2 = 0.f;
; #pragma unroll
;             for (int i = 0; i < 4; ++i)
; #pragma unroll
;                 for (int e = 0; e < 4; ++e) { const float a = bf_lo(w[it][i][e]), b = bf_hi(w[it][i][e]); s1 += a + b; s2 += a * a + b * b; }
;             s1 = sum16(s1); s2 = sum16(s2);
;             const float mean = s1 * (1.0f / 512.0f), rstd = __builtin_amdgcn_rsqf(fmaxf(s2 * (1.0f / 512.0f) - mean * mean, 0.f) + 1e-6f);
; #pragma unroll
;             for (int i = 0; i < 2; ++i) {
;                 const u32x4 ww = wsel[it][i]; u32x4 o;
; #pragma unroll
;                 for (int e = 0; e < 4; ++e) { const int h2 = e >> 1, k2 = (e & 1) * 2;
;                     const float a = (bf_lo(ww[e]) - mean) * rstd * gA[i][h2][k2] + bA[i][h2][k2], b = (bf_hi(ww[e]) - mean) * rstd * gA[i][h2][k2 + 1] + bA[i][h2][k2 + 1];
;                     o[e] = cvt_pk_bf16(a, b); }
;                 *(LAS u32x4*)(lds + q * VN_STRIDE + (l15 + 16 * i) * 16) = o;
;             }
	v_lshlrev_b32_e32 v84, 16, v80
	v_and_b32_e32 v80, 0xffff0000, v80
	v_sub_f32_e32 v84, v84, v89
	v_sub_f32_e32 v80, v80, v89
	v_mul_f32_e32 v84, v84, v88
	v_mul_f32_e32 v80, v80, v88
	v_fma_f32 v84, v8, v84, v12
	v_fma_f32 v80, v9, v80, v13
	v_cvt_pk_bf16_f32 v80, v84, v80
	v_lshlrev_b32_e32 v84, 16, v81
	v_and_b32_e32 v81, 0xffff0000, v81
	v_sub_f32_e32 v84, v84, v89
	v_sub_f32_e32 v81, v81, v89
	v_mul_f32_e32 v84, v84, v88
	v_mul_f32_e32 v81, v81, v88
	v_fma_f32 v84, v10, v84, v14
	v_fma_f32 v81, v11, v81, v15
	v_cvt_pk_bf16_f32 v81, v84, v81
	v_lshlrev_b32_e32 v84, 16, v82
	v_and_b32_e32 v82, 0xffff0000, v82
	v_sub_f32_e32 v84, v84, v89
	v_sub_f32_e32 v82, v82, v89
	v_mul_f32_e32 v84, v84, v88
	v_mul_f32_e32 v82, v82, v88
	v_fma_f32 v84, v0, v84, v4
	v_fma_f32 v82, v1, v82, v5
	v_cvt_pk_bf16_f32 v82, v84, v82
	v_lshlrev_b32_e32 v84, 16, v83
	v_and_b32_e32 v83, 0xffff0000, v83
	v_sub_f32_e32 v84, v84, v89
	v_sub_f32_e32 v83, v83, v89
	v_mul_f32_e32 v84, v84, v88
	v_mul_f32_e32 v83, v83, v88
	v_fma_f32 v84, v2, v84, v6
	v_fma_f32 v83, v3, v83, v7
	v_cvt_pk_bf16_f32 v83, v84, v83
	v_lshlrev_b32_e32 v85, 16, v76
	v_lshlrev_b32_e32 v84, 16, v77
	v_and_b32_e32 v87, 0xffff0000, v76
	v_and_b32_e32 v77, 0xffff0000, v77
	v_pk_mul_f32 v[110:111], v[84:85], v[84:85]
	v_mul_f32_e32 v86, v77, v77
	v_pk_mov_b32 v[110:111], v[110:111], v[84:85] op_sel:[1,0]
	v_mul_f32_e32 v76, v87, v87
	v_pk_add_f32 v[76:77], v[110:111], v[76:77]
	v_mul_f32_e32 v110, v84, v84
	v_pk_add_f32 v[84:85], v[84:85], v[86:87]
	v_lshlrev_b32_e32 v89, 16, v78
	v_mov_b32_e32 v111, v85
	v_mov_b32_e32 v87, v177
	v_mul_f32_e32 v88, v89, v89
	v_mul_f32_e32 v90, v91, v91
	v_pk_add_f32 v[84:85], v[110:111], v[86:87]
	v_mul_f32_e32 v78, v79, v79
	v_pk_add_f32 v[76:77], v[76:77], v[84:85]
	v_pk_add_f32 v[84:85], v[88:89], v[90:91]
	v_and_b32_e32 v73, 0xffff0000, v73
	v_pk_add_f32 v[76:77], v[84:85], v[76:77]
	v_pk_add_f32 v[78:79], v[92:93], v[78:79]
	v_mul_f32_e32 v98, v99, v99
	v_mul_f32_e32 v72, v73, v73
	v_lshlrev_b32_e32 v101, 16, v74
	v_and_b32_e32 v103, 0xffff0000, v74
	v_pk_add_f32 v[76:77], v[78:79], v[76:77]
	v_pk_add_f32 v[78:79], v[94:95], v[96:97]
	v_mul_f32_e32 v100, v101, v101
	v_mul_f32_e32 v102, v103, v103
	v_lshlrev_b32_e32 v105, 16, v75
	v_and_b32_e32 v75, 0xffff0000, v75
	v_pk_add_f32 v[76:77], v[78:79], v[76:77]
	v_pk_add_f32 v[72:73], v[98:99], v[72:73]
	v_mul_f32_e32 v104, v105, v105
	v_mul_f32_e32 v74, v75, v75
	v_lshlrev_b32_e32 v107, 16, v68
	v_and_b32_e32 v109, 0xffff0000, v68
	v_pk_add_f32 v[72:73], v[72:73], v[76:77]
	v_pk_add_f32 v[76:77], v[100:101], v[102:103]
	v_mul_f32_e32 v106, v107, v107
	v_mul_f32_e32 v108, v109, v109
	v_pk_add_f32 v[72:73], v[76:77], v[72:73]
	v_pk_add_f32 v[74:75], v[104:105], v[74:75]
	v_and_b32_e32 v77, 0xffff0000, v70
	v_pk_add_f32 v[72:73], v[74:75], v[72:73]
	v_pk_add_f32 v[74:75], v[106:107], v[108:109]
	v_mul_f32_e32 v76, v77, v77
	v_pk_add_f32 v[72:73], v[74:75], v[72:73]
	v_lshlrev_b32_e32 v75, 16, v69
	v_and_b32_e32 v69, 0xffff0000, v69
	v_mul_f32_e32 v74, v75, v75
	v_mul_f32_e32 v68, v69, v69
	v_pk_add_f32 v[68:69], v[74:75], v[68:69]
	v_lshlrev_b32_e32 v75, 16, v70
	v_mul_f32_e32 v74, v75, v75
	v_lshlrev_b32_e32 v79, 16, v71
	v_and_b32_e32 v71, 0xffff0000, v71
	v_mul_f32_e32 v78, v79, v79
	v_mul_f32_e32 v70, v71, v71
	v_lshlrev_b32_e32 v85, 16, v64
	v_and_b32_e32 v87, 0xffff0000, v64
	v_pk_add_f32 v[68:69], v[68:69], v[72:73]
	v_pk_add_f32 v[72:73], v[74:75], v[76:77]
	v_mul_f32_e32 v84, v85, v85
	v_mul_f32_e32 v86, v87, v87
	v_lshlrev_b32_e32 v89, 16, v65
	v_and_b32_e32 v65, 0xffff0000, v65
	v_pk_add_f32 v[68:69], v[72:73], v[68:69]
	v_pk_add_f32 v[70:71], v[78:79], v[70:71]
	v_mul_f32_e32 v88, v89, v89
	v_mul_f32_e32 v64, v65, v65
	v_lshlrev_b32_e32 v91, 16, v66
	v_and_b32_e32 v93, 0xffff0000, v66
	v_pk_add_f32 v[68:69], v[70:71], v[68:69]
	v_pk_add_f32 v[70:71], v[84:85], v[86:87]
	v_mul_f32_e32 v90, v91, v91
	v_mul_f32_e32 v92, v93, v93
	v_lshlrev_b32_e32 v95, 16, v67
	v_and_b32_e32 v67, 0xffff0000, v67
	v_pk_add_f32 v[68:69], v[70:71], v[68:69]
	v_pk_add_f32 v[64:65], v[88:89], v[64:65]
	v_mul_f32_e32 v94, v95, v95
	v_mul_f32_e32 v66, v67, v67
	v_pk_add_f32 v[64:65], v[64:65], v[68:69]
	v_pk_add_f32 v[68:69], v[90:91], v[92:93]
	v_pk_add_f32 v[66:67], v[94:95], v[66:67]
	v_pk_add_f32 v[64:65], v[68:69], v[64:65]
	ds_write_b128 v163, v[80:83] offset:2944
	v_pk_add_f32 v[64:65], v[66:67], v[64:65]
	v_lshlrev_b32_e32 v69, 16, v55
	v_and_b32_e32 v55, 0xffff0000, v55
	v_mov_b32_dpp v67, v65 quad_perm:[1,0,3,2] row_mask:0xf bank_mask:0xf bound_ctrl:1
	v_mov_b32_dpp v66, v64 quad_perm:[1,0,3,2] row_mask:0xf bank_mask:0xf bound_ctrl:1
	v_pk_add_f32 v[64:65], v[64:65], v[66:67]
	v_mul_f32_e32 v68, v69, v69
	v_lshlrev_b32_e32 v71, 16, v44
	v_mov_b32_dpp v67, v65 quad_perm:[2,3,0,1] row_mask:0xf bank_mask:0xf bound_ctrl:1
	v_mov_b32_dpp v66, v64 quad_perm:[2,3,0,1] row_mask:0xf bank_mask:0xf bound_ctrl:1
	v_pk_add_f32 v[64:65], v[64:65], v[66:67]
	v_and_b32_e32 v73, 0xffff0000, v44
	v_mul_f32_e32 v70, v71, v71
	v_mov_b32_dpp v67, v65 row_half_mirror row_mask:0xf bank_mask:0xf bound_ctrl:1
	v_mov_b32_dpp v66, v64 row_half_mirror row_mask:0xf bank_mask:0xf bound_ctrl:1
	v_pk_add_f32 v[64:65], v[64:65], v[66:67]
	v_mul_f32_e32 v72, v73, v73
	v_lshlrev_b32_e32 v75, 16, v45
	v_mov_b32_dpp v67, v65 row_mirror row_mask:0xf bank_mask:0xf bound_ctrl:1
	v_mov_b32_dpp v66, v64 row_mirror row_mask:0xf bank_mask:0xf bound_ctrl:1
	v_pk_add_f32 v[64:65], v[64:65], v[66:67]
	s_waitcnt vmcnt(3)
; __device__ __forceinline__ unsigned cvt_pk_bf16(float lo, float hi) { unsigned r; asm volatile("v_cvt_pk_bf16_f32 %0, %1, %2" : "=v"(r) : "v"(lo), "v"(hi)); return r; }
; #define LAS __attribute__((address_space(3)))
; __device__ __forceinline__ float bf_lo(unsigned w) { return __uint_as_float(w << 16); }
; __device__ __forceinline__ float bf_hi(unsigned w) { return __uint_as_float(w & 0xffff0000u); }
; __device__ __forceinline__ void mixa_item(const Args& A, int li, int item, LAS unsigned char* lds, int tid, int lane, int wave) {
;     ...
;         for (int it = 0; it < 4; ++it) {
;             const int q = wave * 16 + it * 4 + l4; float s1 = 0.f, s2 = 0.f;
; #pragma unroll
;             for (int i = 0; i < 4; ++i)
; #pragma unroll
;                 for (int e = 0; e < 4; ++e) { const float a = bf_lo(w[it][i][e]), b = bf_hi(w[it][i][e]); s1 += a + b; s2 += a * a + b * b; }
;             s1 = sum16(s1); s2 = sum16(s2);
;             const float mean = s1 * (1.0f / 512.0f), rstd = __builtin_amdgcn_rsqf(fmaxf(s2 * (1.0f / 512.0f) - mean * mean, 0.f) + 1e-6f);
; #pragma unroll
;             for (int i = 0; i < 2; ++i) {
;                 const u32x4 ww = wsel[it][i]; u32x4 o;
; #pragma unroll
;                 for (int e = 0; e < 4; ++e) { const int h2 = e >> 1, k2 = (e & 1) * 2;
;                     const float a = (bf_lo(ww[e]) - mean) * rstd * gA[i][h2][k2] + bA[i][h2][k2], b = (bf_hi(ww[e]) - mean) * rstd * gA[i][h2][k2 + 1] + bA[i][h2][k2 + 1];
;                     o[e] = cvt_pk_bf16(a, b); }
;                 *(LAS u32x4*)(lds + q * VN_STRIDE + (l15 + 16 * i) * 16) = o;
;             }
	v_lshlrev_b32_e32 v66, 16, v60
	v_pk_mul_f32 v[64:65], v[64:65], s[12:13] op_sel_hi:[1,0]
	v_and_b32_e32 v60, 0xffff0000, v60
	v_fma_f32 v64, -v65, v65, v64
	v_max_f32_e32 v64, 0, v64
	v_add_f32_e32 v64, 0x358637bd, v64
	v_rsq_f32_e32 v64, v64
	v_sub_f32_e32 v66, v66, v65
	v_sub_f32_e32 v60, v60, v65
	v_and_b32_e32 v67, 0xffff0000, v54
	v_mul_f32_e32 v66, v66, v64
	v_mul_f32_e32 v60, v60, v64
	v_fma_f32 v66, v24, v66, v28
	v_fma_f32 v60, v25, v60, v29
	v_cvt_pk_bf16_f32 v60, v66, v60
	v_lshlrev_b32_e32 v66, 16, v61
	v_and_b32_e32 v61, 0xffff0000, v61
	v_sub_f32_e32 v66, v66, v65
	v_sub_f32_e32 v61, v61, v65
	v_mul_f32_e32 v66, v66, v64
	v_mul_f32_e32 v61, v61, v64
	v_fma_f32 v66, v26, v66, v30
	v_fma_f32 v61, v27, v61, v31
	v_cvt_pk_bf16_f32 v61, v66, v61
	v_lshlrev_b32_e32 v66, 16, v62
	v_and_b32_e32 v62, 0xffff0000, v62
	v_sub_f32_e32 v66, v66, v65
	v_sub_f32_e32 v62, v62, v65
	v_mul_f32_e32 v66, v66, v64
	v_mul_f32_e32 v62, v62, v64
	v_fma_f32 v66, v16, v66, v20
	v_fma_f32 v62, v17, v62, v21
	v_cvt_pk_bf16_f32 v62, v66, v62
	v_lshlrev_b32_e32 v66, 16, v63
	v_and_b32_e32 v63, 0xffff0000, v63
	v_sub_f32_e32 v63, v63, v65
	v_sub_f32_e32 v66, v66, v65
	v_mul_f32_e32 v63, v63, v64
	v_mul_f32_e32 v66, v66, v64
	v_fma_f32 v63, v19, v63, v23
	v_fma_f32 v66, v18, v66, v22
	v_cvt_pk_bf16_f32 v63, v66, v63
	ds_write_b128 v163, v[60:63] offset:5376
	s_waitcnt vmcnt(2)
	v_lshlrev_b32_e32 v60, 16, v56
	v_and_b32_e32 v56, 0xffff0000, v56
	v_sub_f32_e32 v60, v60, v65
	v_sub_f32_e32 v56, v56, v65
	v_mul_f32_e32 v60, v60, v64
	v_mul_f32_e32 v56, v56, v64
	v_fma_f32 v60, v8, v60, v12
	v_fma_f32 v56, v9, v56, v13
	v_cvt_pk_bf16_f32 v56, v60, v56
	v_lshlrev_b32_e32 v60, 16, v57
	v_and_b32_e32 v57, 0xffff0000, v57
	v_sub_f32_e32 v60, v60, v65
	v_sub_f32_e32 v57, v57, v65
	v_mul_f32_e32 v60, v60, v64
	v_mul_f32_e32 v57, v57, v64
	v_fma_f32 v60, v10, v60, v14
	v_fma_f32 v57, v11, v57, v15
	v_cvt_pk_bf16_f32 v57, v60, v57
	v_lshlrev_b32_e32 v60, 16, v58
	v_and_b32_e32 v58, 0xffff0000, v58
	v_sub_f32_e32 v60, v60, v65
	v_sub_f32_e32 v58, v58, v65
	v_mul_f32_e32 v60, v60, v64
	v_mul_f32_e32 v58, v58, v64
	v_fma_f32 v60, v0, v60, v4
	v_fma_f32 v58, v1, v58, v5
	v_cvt_pk_bf16_f32 v58, v60, v58
	v_lshlrev_b32_e32 v60, 16, v59
	v_and_b32_e32 v59, 0xffff0000, v59
	v_sub_f32_e32 v60, v60, v65
	v_sub_f32_e32 v59, v59, v65
	v_mul_f32_e32 v60, v60, v64
	v_mul_f32_e32 v59, v59, v64
	v_fma_f32 v60, v2, v60, v6
	v_fma_f32 v59, v3, v59, v7
	v_cvt_pk_bf16_f32 v59, v60, v59
	v_lshlrev_b32_e32 v61, 16, v52
	v_lshlrev_b32_e32 v60, 16, v53
	v_and_b32_e32 v63, 0xffff0000, v52
	v_and_b32_e32 v53, 0xffff0000, v53
	v_pk_mul_f32 v[86:87], v[60:61], v[60:61]
	v_mul_f32_e32 v62, v53, v53
	v_pk_mov_b32 v[86:87], v[86:87], v[60:61] op_sel:[1,0]
	v_mul_f32_e32 v52, v63, v63
	v_pk_add_f32 v[52:53], v[86:87], v[52:53]
	v_mul_f32_e32 v86, v60, v60
	v_pk_add_f32 v[60:61], v[60:61], v[62:63]
	v_lshlrev_b32_e32 v65, 16, v54
	v_mov_b32_e32 v87, v61
	v_mov_b32_e32 v63, v177
	v_mul_f32_e32 v64, v65, v65
	v_mul_f32_e32 v66, v67, v67
	v_pk_add_f32 v[60:61], v[86:87], v[62:63]
	v_mul_f32_e32 v54, v55, v55
	v_pk_add_f32 v[52:53], v[52:53], v[60:61]
	v_pk_add_f32 v[60:61], v[64:65], v[66:67]
	v_and_b32_e32 v45, 0xffff0000, v45
	v_pk_add_f32 v[52:53], v[60:61], v[52:53]
	v_pk_add_f32 v[54:55], v[68:69], v[54:55]
	v_mul_f32_e32 v74, v75, v75
	v_mul_f32_e32 v44, v45, v45
	v_lshlrev_b32_e32 v77, 16, v46
	v_and_b32_e32 v79, 0xffff0000, v46
	v_pk_add_f32 v[52:53], v[54:55], v[52:53]
	v_pk_add_f32 v[54:55], v[70:71], v[72:73]
	v_mul_f32_e32 v76, v77, v77
	v_mul_f32_e32 v78, v79, v79
	v_lshlrev_b32_e32 v81, 16, v47
	v_and_b32_e32 v47, 0xffff0000, v47
	v_pk_add_f32 v[52:53], v[54:55], v[52:53]
	v_pk_add_f32 v[44:45], v[74:75], v[44:45]
	v_mul_f32_e32 v80, v81, v81
	v_mul_f32_e32 v46, v47, v47
	v_lshlrev_b32_e32 v83, 16, v36
	v_and_b32_e32 v85, 0xffff0000, v36
	v_pk_add_f32 v[44:45], v[44:45], v[52:53]
	v_pk_add_f32 v[52:53], v[76:77], v[78:79]
	v_mul_f32_e32 v82, v83, v83
	v_mul_f32_e32 v84, v85, v85
	v_pk_add_f32 v[44:45], v[52:53], v[44:45]
	v_pk_add_f32 v[46:47], v[80:81], v[46:47]
	v_and_b32_e32 v53, 0xffff0000, v38
	v_pk_add_f32 v[44:45], v[46:47], v[44:45]
	v_pk_add_f32 v[46:47], v[82:83], v[84:85]
	v_mul_f32_e32 v52, v53, v53
	v_pk_add_f32 v[44:45], v[46:47], v[44:45]
	v_lshlrev_b32_e32 v47, 16, v37
	v_and_b32_e32 v37, 0xffff0000, v37
	v_mul_f32_e32 v46, v47, v47
	v_mul_f32_e32 v36, v37, v37
	v_pk_add_f32 v[36:37], v[46:47], v[36:37]
	v_lshlrev_b32_e32 v47, 16, v38
	v_mul_f32_e32 v46, v47, v47
	v_lshlrev_b32_e32 v55, 16, v39
	v_and_b32_e32 v39, 0xffff0000, v39
	v_mul_f32_e32 v54, v55, v55
	v_mul_f32_e32 v38, v39, v39
	v_lshlrev_b32_e32 v61, 16, v32
	v_and_b32_e32 v63, 0xffff0000, v32
	v_pk_add_f32 v[36:37], v[36:37], v[44:45]
	v_pk_add_f32 v[44:45], v[46:47], v[52:53]
	v_mul_f32_e32 v60, v61, v61
	v_mul_f32_e32 v62, v63, v63
	v_lshlrev_b32_e32 v65, 16, v33
	v_and_b32_e32 v33, 0xffff0000, v33
	v_pk_add_f32 v[36:37], v[44:45], v[36:37]
	v_pk_add_f32 v[38:39], v[54:55], v[38:39]
	v_mul_f32_e32 v64, v65, v65
	v_mul_f32_e32 v32, v33, v33
	v_lshlrev_b32_e32 v67, 16, v34
	v_and_b32_e32 v69, 0xffff0000, v34
	v_pk_add_f32 v[36:37], v[38:39], v[36:37]
	v_pk_add_f32 v[38:39], v[60:61], v[62:63]
	v_mul_f32_e32 v66, v67, v67
	v_mul_f32_e32 v68, v69, v69
	v_lshlrev_b32_e32 v71, 16, v35
	v_and_b32_e32 v35, 0xffff0000, v35
	v_pk_add_f32 v[36:37], v[38:39], v[36:37]
	v_pk_add_f32 v[32:33], v[64:65], v[32:33]
	v_mul_f32_e32 v70, v71, v71
	v_mul_f32_e32 v34, v35, v35
	v_pk_add_f32 v[32:33], v[32:33], v[36:37]
	v_pk_add_f32 v[36:37], v[66:67], v[68:69]
	v_pk_add_f32 v[34:35], v[70:71], v[34:35]
	v_pk_add_f32 v[32:33], v[36:37], v[32:33]
	ds_write_b128 v163, v[56:59] offset:5632
	v_pk_add_f32 v[32:33], v[34:35], v[32:33]
	s_nop 1
	v_mov_b32_dpp v35, v33 quad_perm:[1,0,3,2] row_mask:0xf bank_mask:0xf bound_ctrl:1
	v_mov_b32_dpp v34, v32 quad_perm:[1,0,3,2] row_mask:0xf bank_mask:0xf bound_ctrl:1
	v_pk_add_f32 v[32:33], v[32:33], v[34:35]
	s_nop 1
	v_mov_b32_dpp v35, v33 quad_perm:[2,3,0,1] row_mask:0xf bank_mask:0xf bound_ctrl:1
	v_mov_b32_dpp v34, v32 quad_perm:[2,3,0,1] row_mask:0xf bank_mask:0xf bound_ctrl:1
	v_pk_add_f32 v[32:33], v[32:33], v[34:35]
	s_nop 1
	v_mov_b32_dpp v35, v33 row_half_mirror row_mask:0xf bank_mask:0xf bound_ctrl:1
	v_mov_b32_dpp v34, v32 row_half_mirror row_mask:0xf bank_mask:0xf bound_ctrl:1
	v_pk_add_f32 v[32:33], v[32:33], v[34:35]
	s_nop 1
	v_mov_b32_dpp v35, v33 row_mirror row_mask:0xf bank_mask:0xf bound_ctrl:1
	v_mov_b32_dpp v34, v32 row_mirror row_mask:0xf bank_mask:0xf bound_ctrl:1
	v_pk_add_f32 v[32:33], v[32:33], v[34:35]
	s_waitcnt vmcnt(1)
; __device__ __forceinline__ unsigned cvt_pk_bf16(float lo, float hi) { unsigned r; asm volatile("v_cvt_pk_bf16_f32 %0, %1, %2" : "=v"(r) : "v"(lo), "v"(hi)); return r; }
; #define LAS __attribute__((address_space(3)))
; __device__ __forceinline__ float bf_lo(unsigned w) { return __uint_as_float(w << 16); }
; __device__ __forceinline__ float bf_hi(unsigned w) { return __uint_as_float(w & 0xffff0000u); }
; __device__ __forceinline__ void mixa_item(const Args& A, int li, int item, LAS unsigned char* lds, int tid, int lane, int wave) {
;     ...
;                     const float a = (bf_lo(ww[e]) - mean) * rstd * gA[i][h2][k2] + bA[i][h2][k2], b = (bf_hi(ww[e]) - mean) * rstd * gA[i][h2][k2 + 1] + bA[i][h2][k2 + 1];
;                     o[e] = cvt_pk_bf16(a, b); }
;                 *(LAS u32x4*)(lds + q * VN_STRIDE + (l15 + 16 * i) * 16) = o;
;             }
;         }
;     }
;     __syncthreads();
;     const int gl = wave >> 1, ph = wave & 1, gg = gh * 4 + gl, g = lane >> 4, i16 = lane & 15;
;     f32x4 acc[4][4];
; #pragma unroll
;     for (int a = 0; a < 4; ++a)
; #pragma unroll
;         for (int b = 0; b < 4; ++b) acc[a][b] = (f32x4){0.f, 0.f, 0.f, 0.f};
;     const LAS unsigned char* trb = lds + (4 * g + (i16 >> 2)) * VN_STRIDE + (gl * 64 + 4 * (i16 & 3)) * 2;
;     const bf16_t* wb = spw + ((size_t)gg * 128 + ph * 64 + i16) * 128 + 4 * g;
; #pragma unroll
;     for (int ks = 0; ks < 4; ++ks) {
;         bf16x8 af[4], bfr[4];
; #pragma unroll
;         for (int cb = 0; cb < 4; ++cb) af[cb] = tr_pair(trb + (32 * ks) * VN_STRIDE + cb * 32, trb + (32 * ks + 16) * VN_STRIDE + cb * 32);
; #pragma unroll
;         for (int pb = 0; pb < 4; ++pb) { const s16x4 lo = *(const s16x4*)(wb + pb * 16 * 128 + 32 * ks), hi = *(const s16x4*)(wb + pb * 16 * 128 + 32 * ks + 16);
;             bfr[pb] = (bf16x8){lo[0], lo[1], lo[2], lo[3], hi[0], hi[1], hi[2], hi[3]}; }
; #pragma unroll
;         for (int cb = 0; cb < 4; ++cb)
; #pragma unroll
;             for (int pb = 0; pb < 4; ++pb) acc[cb][pb] = __builtin_amdgcn_mfma_f32_16x16x32_bf16(af[cb], bfr[pb], acc[cb][pb], 0, 0, 0);
	v_lshlrev_b32_e32 v34, 16, v48
	v_pk_mul_f32 v[32:33], v[32:33], s[12:13] op_sel_hi:[1,0]
	s_nop 0
	v_fma_f32 v32, -v33, v33, v32
	v_max_f32_e32 v32, 0, v32
	v_add_f32_e32 v32, 0x358637bd, v32
	v_rsq_f32_e32 v32, v32
	v_sub_f32_e32 v34, v34, v33
	v_mul_f32_e32 v34, v34, v32
	v_fma_f32 v24, v24, v34, v28
	v_and_b32_e32 v28, 0xffff0000, v48
	v_sub_f32_e32 v28, v28, v33
	v_mul_f32_e32 v28, v28, v32
	v_fma_f32 v25, v25, v28, v29
	v_cvt_pk_bf16_f32 v24, v24, v25
	v_lshlrev_b32_e32 v25, 16, v49
	v_sub_f32_e32 v25, v25, v33
	v_mul_f32_e32 v25, v25, v32
	v_fma_f32 v25, v26, v25, v30
	v_and_b32_e32 v26, 0xffff0000, v49
	v_sub_f32_e32 v26, v26, v33
	v_mul_f32_e32 v26, v26, v32
	v_fmac_f32_e32 v31, v27, v26
	v_lshlrev_b32_e32 v26, 16, v50
	v_sub_f32_e32 v26, v26, v33
	v_mul_f32_e32 v26, v26, v32
	v_fma_f32 v16, v16, v26, v20
	v_and_b32_e32 v20, 0xffff0000, v50
	v_sub_f32_e32 v20, v20, v33
	v_mul_f32_e32 v20, v20, v32
	v_cvt_pk_bf16_f32 v25, v25, v31
	v_fma_f32 v17, v17, v20, v21
	v_cvt_pk_bf16_f32 v26, v16, v17
	v_lshlrev_b32_e32 v16, 16, v51
	v_sub_f32_e32 v16, v16, v33
	v_and_b32_e32 v17, 0xffff0000, v51
	v_mul_f32_e32 v16, v16, v32
	v_sub_f32_e32 v17, v17, v33
	v_fma_f32 v16, v18, v16, v22
	v_mul_f32_e32 v17, v17, v32
	v_fmac_f32_e32 v23, v19, v17
	v_cvt_pk_bf16_f32 v27, v16, v23
	s_waitcnt vmcnt(0)
	v_lshlrev_b32_e32 v16, 16, v40
	v_sub_f32_e32 v16, v16, v33
	v_mul_f32_e32 v16, v16, v32
	v_fma_f32 v8, v8, v16, v12
	v_and_b32_e32 v12, 0xffff0000, v40
	v_sub_f32_e32 v12, v12, v33
	v_mul_f32_e32 v12, v12, v32
	v_fma_f32 v9, v9, v12, v13
	ds_write_b128 v163, v[24:27] offset:8064
	v_cvt_pk_bf16_f32 v8, v8, v9
	v_lshlrev_b32_e32 v9, 16, v41
	v_sub_f32_e32 v9, v9, v33
	v_mul_f32_e32 v9, v9, v32
	v_fma_f32 v9, v10, v9, v14
	v_and_b32_e32 v10, 0xffff0000, v41
	v_sub_f32_e32 v10, v10, v33
	v_mul_f32_e32 v10, v10, v32
	v_fmac_f32_e32 v15, v11, v10
	v_lshlrev_b32_e32 v10, 16, v42
	v_sub_f32_e32 v10, v10, v33
	v_mul_f32_e32 v10, v10, v32
	v_fma_f32 v0, v0, v10, v4
	v_and_b32_e32 v4, 0xffff0000, v42
	v_sub_f32_e32 v4, v4, v33
	v_mul_f32_e32 v4, v4, v32
	v_fma_f32 v1, v1, v4, v5
	v_cvt_pk_bf16_f32 v9, v9, v15
	v_cvt_pk_bf16_f32 v10, v0, v1
	v_lshlrev_b32_e32 v0, 16, v43
	v_and_b32_e32 v1, 0xffff0000, v43
	v_sub_f32_e32 v0, v0, v33
	v_sub_f32_e32 v1, v1, v33
	v_lshl_add_u64 v[30:31], v[128:129], 0, s[20:21]
	v_mul_f32_e32 v0, v0, v32
	v_mul_f32_e32 v1, v1, v32
	v_add_co_u32_e32 v32, vcc, s14, v30
	s_movk_i32 s14, 0x2000
	s_nop 0
	v_addc_co_u32_e32 v33, vcc, 0, v31, vcc
	v_add_co_u32_e32 v28, vcc, s14, v30
	s_movk_i32 s14, 0x3000
	s_nop 0
	v_addc_co_u32_e32 v29, vcc, 0, v31, vcc
	v_add_co_u32_e32 v34, vcc, s14, v30
	v_fma_f32 v0, v2, v0, v6
	v_fmac_f32_e32 v7, v3, v1
	v_addc_co_u32_e32 v35, vcc, 0, v31, vcc
	v_cvt_pk_bf16_f32 v11, v0, v7
	ds_write_b128 v163, v[8:11] offset:8320
	s_waitcnt lgkmcnt(0)
	s_barrier
	global_load_dwordx2 v[6:7], v[30:31], off
	global_load_dwordx2 v[8:9], v[30:31], off offset:32
	global_load_dwordx2 v[12:13], v[28:29], off offset:-4096
	global_load_dwordx2 v[14:15], v[32:33], off offset:32
	ds_read_b64_tr_b16 v[36:37], v115
	ds_read_b64_tr_b16 v[40:41], v115 offset:32
	ds_read_b64_tr_b16 v[20:21], v115 offset:64
	ds_read_b64_tr_b16 v[16:17], v115 offset:96
	ds_read_b64_tr_b16 v[38:39], v115 offset:10752
	ds_read_b64_tr_b16 v[42:43], v115 offset:10784
	ds_read_b64_tr_b16 v[22:23], v115 offset:10816
	ds_read_b64_tr_b16 v[18:19], v115 offset:10848
	global_load_dwordx2 v[24:25], v[34:35], off
	global_load_dwordx2 v[0:1], v[30:31], off offset:64
	global_load_dwordx2 v[2:3], v[30:31], off offset:96
	global_load_dwordx2 v[48:49], v[28:29], off
	global_load_dwordx2 v[50:51], v[28:29], off offset:32
	global_load_dwordx2 v[52:53], v[28:29], off offset:64
	global_load_dwordx2 v[56:57], v[32:33], off offset:64
	global_load_dwordx2 v[58:59], v[32:33], off offset:96
	global_load_dwordx2 v[4:5], v[32:33], off offset:128
	global_load_dwordx2 v[26:27], v[34:35], off offset:32
	s_waitcnt vmcnt(12) lgkmcnt(3)
	v_mfma_f32_16x16x32_bf16 v[44:47], v[36:39], v[6:9], 0
	global_load_dwordx2 v[68:69], v[34:35], off offset:64
	global_load_dwordx2 v[70:71], v[34:35], off offset:96
	global_load_dwordx2 v[72:73], v[34:35], off offset:128
	global_load_dwordx2 v[10:11], v[32:33], off offset:224
	ds_read_b64_tr_b16 v[98:99], v115 offset:21504
	ds_read_b64_tr_b16 v[100:101], v115 offset:32256
	s_lshl_b32 s20, s48, 6
	s_waitcnt vmcnt(14)
	v_mfma_f32_16x16x32_bf16 v[60:63], v[36:39], v[12:15], 0
	s_lshl_b32 s14, s48, 7
	s_ashr_i32 s21, s20, 31
	s_lshl_b64 s[20:21], s[20:21], 1
	s_waitcnt vmcnt(9)
	v_mfma_f32_16x16x32_bf16 v[64:67], v[36:39], v[48:51], 0
	s_ashr_i32 s22, s14, 31
	s_waitcnt vmcnt(4)
	v_mfma_f32_16x16x32_bf16 v[36:39], v[36:39], v[24:27], 0
	s_waitcnt lgkmcnt(4)
	v_mfma_f32_16x16x32_bf16 v[74:77], v[40:43], v[6:9], 0
	v_mfma_f32_16x16x32_bf16 v[78:81], v[40:43], v[12:15], 0
	v_mfma_f32_16x16x32_bf16 v[82:85], v[40:43], v[48:51], 0
	v_mfma_f32_16x16x32_bf16 v[40:43], v[40:43], v[24:27], 0
	s_waitcnt lgkmcnt(3)
	v_mfma_f32_16x16x32_bf16 v[86:89], v[20:23], v[6:9], 0
	v_mfma_f32_16x16x32_bf16 v[90:93], v[20:23], v[12:15], 0
	v_mfma_f32_16x16x32_bf16 v[94:97], v[20:23], v[48:51], 0
	v_mfma_f32_16x16x32_bf16 v[20:23], v[20:23], v[24:27], 0
	s_waitcnt lgkmcnt(2)
	v_mfma_f32_16x16x32_bf16 v[6:9], v[16:19], v[6:9], 0
	v_mfma_f32_16x16x32_bf16 v[12:15], v[16:19], v[12:15], 0
	v_mfma_f32_16x16x32_bf16 v[48:51], v[16:19], v[48:51], 0
	v_mfma_f32_16x16x32_bf16 v[16:19], v[16:19], v[24:27], 0
	ds_read_b64_tr_b16 v[24:25], v115 offset:21536
	ds_read_b64_tr_b16 v[102:103], v115 offset:21568
	ds_read_b64_tr_b16 v[106:107], v115 offset:21600
	ds_read_b64_tr_b16 v[26:27], v115 offset:32288
	ds_read_b64_tr_b16 v[104:105], v115 offset:32320
	ds_read_b64_tr_b16 v[108:109], v115 offset:32352
	global_load_dwordx2 v[54:55], v[28:29], off offset:96
	global_load_dwordx2 v[194:195], v[28:29], off offset:128
	global_load_dwordx2 v[196:197], v[28:29], off offset:160
	global_load_dwordx2 v[198:199], v[28:29], off offset:192
	s_waitcnt lgkmcnt(6)
; __device__ __forceinline__ void mixa_item(const Args& A, int li, int item, LAS unsigned char* lds, int tid, int lane, int wave) {
;     ...
;     for (int ks = 0; ks < 4; ++ks) {
;         bf16x8 af[4], bfr[4];
; #pragma unroll
;         for (int cb = 0; cb < 4; ++cb) af[cb] = tr_pair(trb + (32 * ks) * VN_STRIDE + cb * 32, trb + (32 * ks + 16) * VN_STRIDE + cb * 32);
; #pragma unroll
;         for (int pb = 0; pb < 4; ++pb) { const s16x4 lo = *(const s16x4*)(wb + pb * 16 * 128 + 32 * ks), hi = *(const s16x4*)(wb + pb * 16 * 128 + 32 * ks + 16);
;             bfr[pb] = (bf16x8){lo[0], lo[1], lo[2], lo[3], hi[0], hi[1], hi[2], hi[3]}; }
; #pragma unroll
;         for (int cb = 0; cb < 4; ++cb)
; #pragma unroll
;             for (int pb = 0; pb < 4; ++pb) acc[cb][pb] = __builtin_amdgcn_mfma_f32_16x16x32_bf16(af[cb], bfr[pb], acc[cb][pb], 0, 0, 0);
;     }
;     u32x2 uw[4][4]; float sbv[4];
; #pragma unroll
;     for (int pb = 0; pb < 4; ++pb) { const int p = ph * 64 + pb * 16 + i16; sbv[pb] = spb[gg * 128 + p];
; #pragma unroll
;         for (int cb = 0; cb < 4; ++cb) uw[pb][cb] = *(const u32x2*)(UV + (size_t)(row0 + p) * 1024 + gg * 64 + cb * 16 + 4 * g); }
	v_mfma_f32_16x16x32_bf16 v[44:47], v[98:101], v[0:3], v[44:47]
	v_mfma_f32_16x16x32_bf16 v[60:63], v[98:101], v[56:59], v[60:63]
	s_waitcnt vmcnt(3)
	v_mfma_f32_16x16x32_bf16 v[64:67], v[98:101], v[52:55], v[64:67]
	v_mfma_f32_16x16x32_bf16 v[36:39], v[98:101], v[68:71], v[36:39]
	s_waitcnt lgkmcnt(2)
	v_mfma_f32_16x16x32_bf16 v[98:101], v[24:27], v[0:3], v[74:77]
	v_mfma_f32_16x16x32_bf16 v[76:79], v[24:27], v[56:59], v[78:81]
	v_mfma_f32_16x16x32_bf16 v[80:83], v[24:27], v[52:55], v[82:85]
	v_mfma_f32_16x16x32_bf16 v[24:27], v[24:27], v[68:71], v[40:43]
	s_waitcnt lgkmcnt(1)
	v_mfma_f32_16x16x32_bf16 v[40:43], v[102:105], v[0:3], v[86:89]
	v_mfma_f32_16x16x32_bf16 v[84:87], v[102:105], v[56:59], v[90:93]
	v_mfma_f32_16x16x32_bf16 v[88:91], v[102:105], v[52:55], v[94:97]
	v_mfma_f32_16x16x32_bf16 v[20:23], v[102:105], v[68:71], v[20:23]
	s_waitcnt lgkmcnt(0)
	v_mfma_f32_16x16x32_bf16 v[0:3], v[106:109], v[0:3], v[6:9]
	v_mfma_f32_16x16x32_bf16 v[12:15], v[106:109], v[56:59], v[12:15]
	v_mfma_f32_16x16x32_bf16 v[48:51], v[106:109], v[52:55], v[48:51]
	global_load_dwordx2 v[52:53], v[30:31], off offset:128
	global_load_dwordx2 v[54:55], v[30:31], off offset:160
	v_mfma_f32_16x16x32_bf16 v[16:19], v[106:109], v[68:71], v[16:19]
	ds_read_b64_tr_b16 v[58:59], v115 offset:53760
	ds_read_b64_tr_b16 v[56:57], v115 offset:43008
	ds_read_b64_tr_b16 v[68:69], v115 offset:43040
	ds_read_b64_tr_b16 v[92:93], v115 offset:43072
	ds_read_b64_tr_b16 v[102:103], v115 offset:43104
	ds_read_b64_tr_b16 v[70:71], v115 offset:53792
	ds_read_b64_tr_b16 v[94:95], v115 offset:53824
	ds_read_b64_tr_b16 v[104:105], v115 offset:53856
	global_load_dwordx2 v[106:107], v[30:31], off offset:192
	global_load_dwordx2 v[108:109], v[30:31], off offset:224
	global_load_dwordx2 v[6:7], v[32:33], off offset:160
	global_load_dwordx2 v[8:9], v[32:33], off offset:192
	s_waitcnt vmcnt(1) lgkmcnt(6)
	v_mfma_f32_16x16x32_bf16 v[30:33], v[56:59], v[4:7], v[60:63]
	v_mfma_f32_16x16x32_bf16 v[60:63], v[56:59], v[194:197], v[64:67]
	global_load_dwordx2 v[74:75], v[34:35], off offset:160
	s_nop 1
	global_load_dwordx2 v[64:65], v[34:35], off offset:192
	global_load_dwordx2 v[66:67], v[34:35], off offset:224
	v_mfma_f32_16x16x32_bf16 v[44:47], v[56:59], v[52:55], v[44:47]
	s_waitcnt vmcnt(2)
	v_mfma_f32_16x16x32_bf16 v[34:37], v[56:59], v[72:75], v[36:39]
	s_waitcnt lgkmcnt(2)
	v_mfma_f32_16x16x32_bf16 v[56:59], v[68:71], v[52:55], v[98:101]
	v_mfma_f32_16x16x32_bf16 v[76:79], v[68:71], v[4:7], v[76:79]
	v_mfma_f32_16x16x32_bf16 v[80:83], v[68:71], v[194:197], v[80:83]
	v_mfma_f32_16x16x32_bf16 v[24:27], v[68:71], v[72:75], v[24:27]
	s_waitcnt lgkmcnt(1)
	v_mfma_f32_16x16x32_bf16 v[38:41], v[92:95], v[52:55], v[40:43]
	v_mfma_f32_16x16x32_bf16 v[68:71], v[92:95], v[4:7], v[84:87]
	v_mfma_f32_16x16x32_bf16 v[84:87], v[92:95], v[194:197], v[88:91]
	v_mfma_f32_16x16x32_bf16 v[88:91], v[92:95], v[72:75], v[20:23]
	s_waitcnt lgkmcnt(0)
	v_mfma_f32_16x16x32_bf16 v[52:55], v[102:105], v[52:55], v[0:3]
	s_nop 2
	ds_read_b64_tr_b16 v[0:1], v115 offset:64512
	ds_read_b64_tr_b16 v[2:3], v148
	v_mfma_f32_16x16x32_bf16 v[92:95], v[102:105], v[4:7], v[12:15]
	v_mfma_f32_16x16x32_bf16 v[48:51], v[102:105], v[194:197], v[48:51]
	v_mfma_f32_16x16x32_bf16 v[72:75], v[102:105], v[72:75], v[16:19]
	ds_read_b64_tr_b16 v[4:5], v115 offset:64544
	ds_read_b64_tr_b16 v[96:97], v115 offset:64576
	ds_read_b64_tr_b16 v[100:101], v115 offset:64608
	ds_read_b64_tr_b16 v[6:7], v149
	ds_read_b64_tr_b16 v[98:99], v150
	ds_read_b64_tr_b16 v[102:103], v151
	global_load_dwordx2 v[200:201], v[28:29], off offset:224
	v_lshl_add_u64 v[104:105], v[118:119], 0, s[20:21]
	s_waitcnt lgkmcnt(6)
	v_mfma_f32_16x16x32_bf16 v[194:197], v[0:3], v[8:11], v[30:33]
	s_nop 2
	v_or_b32_e32 v32, s11, v114
	s_waitcnt lgkmcnt(2)
	v_mfma_f32_16x16x32_bf16 v[56:59], v[4:7], v[106:109], v[56:59]
	v_ashrrev_i32_e32 v33, 31, v32
	v_lshl_add_u64 v[30:31], v[116:117], 0, s[20:21]
	v_mfma_f32_16x16x32_bf16 v[76:79], v[4:7], v[8:11], v[76:79]
	s_waitcnt vmcnt(0)
	v_mfma_f32_16x16x32_bf16 v[20:23], v[4:7], v[198:201], v[80:83]
	v_mfma_f32_16x16x32_bf16 v[4:7], v[4:7], v[64:67], v[24:27]
	s_nop 2
	v_or_b32_e32 v24, s14, v114
	s_waitcnt lgkmcnt(1)
	v_mfma_f32_16x16x32_bf16 v[16:19], v[96:99], v[198:201], v[84:87]
	v_ashrrev_i32_e32 v25, 31, v24
	v_lshl_add_u64 v[24:25], v[24:25], 2, s[26:27]
	s_nop 0
	v_lshlrev_b64 v[84:85], 11, v[32:33]
	v_lshl_add_u64 v[28:29], v[30:31], 0, v[84:85]
	v_mfma_f32_16x16x32_bf16 v[42:45], v[0:3], v[106:109], v[44:47]
	global_load_dwordx2 v[86:87], v[28:29], off
	v_lshl_add_u64 v[84:85], v[104:105], 0, v[84:85]
	s_nop 0
	global_load_dword v46, v[24:25], off
	v_mfma_f32_16x16x32_bf16 v[60:63], v[0:3], v[198:201], v[60:63]
	s_waitcnt vmcnt(0)
	s_nop 1
	v_pk_add_f32 v[42:43], v[42:43], v[46:47] op_sel_hi:[1,0]
	v_mfma_f32_16x16x32_bf16 v[12:15], v[0:3], v[64:67], v[34:37]
	v_add_f32_e64 v44, v44, v46
	v_add_f32_e64 v45, v45, v46
	v_mfma_f32_16x16x32_bf16 v[0:3], v[96:99], v[64:67], v[88:91]
	v_or_b32_e32 v34, s11, v152
	v_ashrrev_i32_e32 v35, 31, v34
	v_lshlrev_b64 v[34:35], 11, v[34:35]
	global_load_dwordx2 v[88:89], v[28:29], off offset:32
	global_load_dwordx2 v[90:91], v[28:29], off offset:64
	s_waitcnt lgkmcnt(0)
; __device__ __forceinline__ unsigned cvt_pk_bf16(float lo, float hi) { unsigned r; asm volatile("v_cvt_pk_bf16_f32 %0, %1, %2" : "=v"(r) : "v"(lo), "v"(hi)); return r; }
; __device__ __forceinline__ float bf_lo(unsigned w) { return __uint_as_float(w << 16); }
; __device__ __forceinline__ float bf_hi(unsigned w) { return __uint_as_float(w & 0xffff0000u); }
; __device__ __forceinline__ void mixa_item(const Args& A, int li, int item, LAS unsigned char* lds, int tid, int lane, int wave) {
;     ...
;     u32x2 uw[4][4]; float sbv[4];
; #pragma unroll
;     for (int pb = 0; pb < 4; ++pb) { const int p = ph * 64 + pb * 16 + i16; sbv[pb] = spb[gg * 128 + p];
; #pragma unroll
;         for (int cb = 0; cb < 4; ++cb) uw[pb][cb] = *(const u32x2*)(UV + (size_t)(row0 + p) * 1024 + gg * 64 + cb * 16 + 4 * g); }
;     asm volatile("" ::: "memory");
; #pragma unroll
;     for (int pb = 0; pb < 4; ++pb) {
;         const int p = ph * 64 + pb * 16 + i16;
; #pragma unroll
;         for (int cb = 0; cb < 4; ++cb) {
;             const size_t off = (size_t)(row0 + p) * 1024 + gg * 64 + cb * 16 + 4 * g;
;             const f32x4 sv = acc[cb][pb] + sbv[pb];
;             u32x2 o; o.x = cvt_pk_bf16(bf_lo(uw[pb][cb].x) * sv[0], bf_hi(uw[pb][cb].x) * sv[1]); o.y = cvt_pk_bf16(bf_lo(uw[pb][cb].y) * sv[2], bf_hi(uw[pb][cb].y) * sv[3]);
;             *(u32x2*)(CAT + off) = o;
;         }
	v_mfma_f32_16x16x32_bf16 v[24:27], v[100:103], v[198:201], v[48:51]
	v_lshl_add_u64 v[34:35], v[30:31], 0, v[34:35]
	s_nop 1
	global_load_dwordx2 v[48:49], v[28:29], off offset:96
	v_mov_b32_e32 v29, s22
	v_or_b32_e32 v28, s14, v114
	v_lshl_add_u64 v[28:29], v[28:29], 2, s[26:27]
	global_load_dword v50, v[28:29], off offset:64
	v_mfma_f32_16x16x32_bf16 v[68:71], v[96:99], v[8:11], v[68:71]
	v_and_b32_e32 v33, 0xffff0000, v86
	v_mul_f32_e32 v33, v43, v33
	v_mfma_f32_16x16x32_bf16 v[80:83], v[100:103], v[8:11], v[92:95]
	v_mfma_f32_16x16x32_bf16 v[8:11], v[100:103], v[64:67], v[72:75]
	global_load_dwordx2 v[64:65], v[34:35], off
	global_load_dwordx2 v[66:67], v[34:35], off offset:32
	s_nop 0
	global_load_dwordx2 v[72:73], v[34:35], off offset:64
	global_load_dwordx2 v[74:75], v[34:35], off offset:96
	v_or_b32_e32 v34, s11, v153
	v_ashrrev_i32_e32 v35, 31, v34
	v_lshlrev_b64 v[34:35], 11, v[34:35]
	v_lshl_add_u64 v[34:35], v[30:31], 0, v[34:35]
	v_mfma_f32_16x16x32_bf16 v[38:41], v[96:99], v[106:109], v[38:41]
	v_mfma_f32_16x16x32_bf16 v[52:55], v[100:103], v[106:109], v[52:55]
	global_load_dwordx2 v[92:93], v[34:35], off
	global_load_dwordx2 v[94:95], v[34:35], off offset:32
	global_load_dwordx2 v[96:97], v[34:35], off offset:64
	global_load_dwordx2 v[98:99], v[34:35], off offset:96
	global_load_dword v100, v[28:29], off offset:128
	s_nop 0
	global_load_dword v28, v[28:29], off offset:192
	v_or_b32_e32 v34, s11, v154
	v_ashrrev_i32_e32 v35, 31, v34
	v_lshlrev_b64 v[34:35], 11, v[34:35]
	v_lshl_add_u64 v[30:31], v[30:31], 0, v[34:35]
	global_load_dwordx2 v[102:103], v[30:31], off
	global_load_dwordx2 v[36:37], v[30:31], off offset:32
	global_load_dwordx2 v[34:35], v[30:31], off offset:64
	s_nop 0
	global_load_dwordx2 v[30:31], v[30:31], off offset:96
	v_lshlrev_b32_e32 v29, 16, v86
	v_mul_f32_e32 v29, v42, v29
	v_cvt_pk_bf16_f32 v42, v29, v33
	v_lshlrev_b32_e32 v29, 16, v87
	v_and_b32_e32 v33, 0xffff0000, v87
	v_mul_f32_e32 v29, v44, v29
	v_mul_f32_e32 v33, v45, v33
	v_cvt_pk_bf16_f32 v43, v29, v33
	v_pk_add_f32 v[44:45], v[56:57], v[46:47] op_sel_hi:[1,0]
	global_store_dwordx2 v[84:85], v[42:43], off
	v_pk_add_f32 v[42:43], v[58:59], v[46:47] op_sel_hi:[1,0]
	v_pk_add_f32 v[38:39], v[38:39], v[46:47] op_sel_hi:[1,0]
	v_pk_add_f32 v[40:41], v[40:41], v[46:47] op_sel_hi:[1,0]
	s_waitcnt vmcnt(18)
	v_lshlrev_b32_e32 v29, 16, v88
	v_and_b32_e32 v33, 0xffff0000, v88
	v_mul_f32_e32 v29, v44, v29
	v_mul_f32_e32 v33, v45, v33
	v_cvt_pk_bf16_f32 v44, v29, v33
	v_lshlrev_b32_e32 v29, 16, v89
	v_and_b32_e32 v33, 0xffff0000, v89
	v_mul_f32_e32 v29, v42, v29
	v_mul_f32_e32 v33, v43, v33
	v_cvt_pk_bf16_f32 v45, v29, v33
	s_waitcnt vmcnt(17)
	v_lshlrev_b32_e32 v29, 16, v90
	v_and_b32_e32 v33, 0xffff0000, v90
	v_mul_f32_e32 v29, v38, v29
	v_mul_f32_e32 v33, v39, v33
	global_store_dwordx2 v[84:85], v[44:45], off offset:32
	v_cvt_pk_bf16_f32 v38, v29, v33
	v_lshlrev_b32_e32 v29, 16, v91
	v_and_b32_e32 v33, 0xffff0000, v91
	v_mul_f32_e32 v29, v40, v29
	v_mul_f32_e32 v33, v41, v33
	v_cvt_pk_bf16_f32 v39, v29, v33
	v_pk_add_f32 v[40:41], v[52:53], v[46:47] op_sel_hi:[1,0]
	s_waitcnt vmcnt(17)
	v_lshlrev_b32_e32 v29, 16, v48
	v_and_b32_e32 v33, 0xffff0000, v48
	v_mul_f32_e32 v29, v40, v29
	v_mul_f32_e32 v33, v41, v33
	global_store_dwordx2 v[84:85], v[38:39], off offset:64
	v_pk_add_f32 v[38:39], v[54:55], v[46:47] op_sel_hi:[1,0]
	v_cvt_pk_bf16_f32 v40, v29, v33
	v_lshlrev_b32_e32 v29, 16, v49
	v_and_b32_e32 v33, 0xffff0000, v49
	v_mul_f32_e32 v29, v38, v29
	v_mul_f32_e32 v33, v39, v33
	v_cvt_pk_bf16_f32 v41, v29, v33
	v_or_b32_e32 v38, 16, v32
	s_waitcnt vmcnt(17)
	v_pk_add_f32 v[42:43], v[194:195], v[50:51] op_sel_hi:[1,0]
	s_waitcnt vmcnt(16)
	v_lshlrev_b32_e32 v29, 16, v64
	v_and_b32_e32 v33, 0xffff0000, v64
	v_ashrrev_i32_e32 v39, 31, v38
	v_mul_f32_e32 v29, v42, v29
	v_mul_f32_e32 v33, v43, v33
	global_store_dwordx2 v[84:85], v[40:41], off offset:96
	v_lshlrev_b64 v[38:39], 11, v[38:39]
	v_pk_add_f32 v[40:41], v[196:197], v[50:51] op_sel_hi:[1,0]
	v_cvt_pk_bf16_f32 v42, v29, v33
	v_lshlrev_b32_e32 v29, 16, v65
	v_and_b32_e32 v33, 0xffff0000, v65
	v_lshl_add_u64 v[38:39], v[104:105], 0, v[38:39]
	v_mul_f32_e32 v29, v40, v29
	v_mul_f32_e32 v33, v41, v33
	v_cvt_pk_bf16_f32 v43, v29, v33
	global_store_dwordx2 v[38:39], v[42:43], off
	v_pk_add_f32 v[42:43], v[76:77], v[50:51] op_sel_hi:[1,0]
	s_waitcnt vmcnt(17)
	v_lshlrev_b32_e32 v29, 16, v66
	v_and_b32_e32 v33, 0xffff0000, v66
	v_mul_f32_e32 v29, v42, v29
	v_mul_f32_e32 v33, v43, v33
	v_pk_add_f32 v[40:41], v[78:79], v[50:51] op_sel_hi:[1,0]
	v_cvt_pk_bf16_f32 v42, v29, v33
	v_lshlrev_b32_e32 v29, 16, v67
	v_and_b32_e32 v33, 0xffff0000, v67
	v_mul_f32_e32 v29, v40, v29
	v_mul_f32_e32 v33, v41, v33
	v_cvt_pk_bf16_f32 v43, v29, v33
	global_store_dwordx2 v[38:39], v[42:43], off offset:32
	v_pk_add_f32 v[42:43], v[68:69], v[50:51] op_sel_hi:[1,0]
	s_waitcnt vmcnt(17)
	v_lshlrev_b32_e32 v29, 16, v72
	v_and_b32_e32 v33, 0xffff0000, v72
	v_mul_f32_e32 v29, v42, v29
	v_mul_f32_e32 v33, v43, v33
	v_pk_add_f32 v[40:41], v[70:71], v[50:51] op_sel_hi:[1,0]
	v_cvt_pk_bf16_f32 v42, v29, v33
	v_lshlrev_b32_e32 v29, 16, v73
	v_and_b32_e32 v33, 0xffff0000, v73
	v_mul_f32_e32 v29, v40, v29
	v_mul_f32_e32 v33, v41, v33
	v_cvt_pk_bf16_f32 v43, v29, v33
	global_store_dwordx2 v[38:39], v[42:43], off offset:64
	v_pk_add_f32 v[42:43], v[80:81], v[50:51] op_sel_hi:[1,0]
	s_waitcnt vmcnt(17)
; __device__ __forceinline__ unsigned cvt_pk_bf16(float lo, float hi) { unsigned r; asm volatile("v_cvt_pk_bf16_f32 %0, %1, %2" : "=v"(r) : "v"(lo), "v"(hi)); return r; }
; #define LAS __attribute__((address_space(3)))
; __device__ __forceinline__ float bf_lo(unsigned w) { return __uint_as_float(w << 16); }
; __device__ __forceinline__ float bf_hi(unsigned w) { return __uint_as_float(w & 0xffff0000u); }
; __device__ __forceinline__ void mixa_item(const Args& A, int li, int item, LAS unsigned char* lds, int tid, int lane, int wave) {
;     ...
;     for (int pb = 0; pb < 4; ++pb) {
;         const int p = ph * 64 + pb * 16 + i16;
; #pragma unroll
;         for (int cb = 0; cb < 4; ++cb) {
;             const size_t off = (size_t)(row0 + p) * 1024 + gg * 64 + cb * 16 + 4 * g;
;             const f32x4 sv = acc[cb][pb] + sbv[pb];
;             u32x2 o; o.x = cvt_pk_bf16(bf_lo(uw[pb][cb].x) * sv[0], bf_hi(uw[pb][cb].x) * sv[1]); o.y = cvt_pk_bf16(bf_lo(uw[pb][cb].y) * sv[2], bf_hi(uw[pb][cb].y) * sv[3]);
;             *(u32x2*)(CAT + off) = o;
;         }
;     }
;     __syncthreads();
; __device__ __forceinline__ void mixb_item(const Args& A, int li, int item, LAS unsigned char* lds, int tid, int lane, int wave) {
;     const int row0 = item * 32, bb = row0 >> 13, pos0 = row0 & 8191;
;     const bf16_t* Gb = (const bf16_t*)(A.ws + WS_GB); bf16_t* CAT = (bf16_t*)(A.ws + WS_CAT);
;     const float* cw = A.in[10] + (size_t)li * 31 * 512; const float* cb = A.in[11] + li * 512; const float* ng = A.in[12] + li * 512; const float* nb = A.in[13] + li * 512;
;     LAS float* cv = (LAS float*)(lds + 65536);
;     {
;         u32x4 st[8];
; #pragma unroll
;         for (int i = 0; i < 8; ++i) { const int idx = tid + NTHR * i, row = idx >> 6, ch = idx & 63, pos = pos0 - 15 + row; const bool ok = idx < 62 * 64 && pos >= 0 && pos < SEQ;
;             st[i] = ok ? *(const u32x4*)(Gb + ((size_t)bb * SEQ + (ok ? pos : pos0)) * 512 + ch * 8) : (u32x4){0u, 0u, 0u, 0u}; }
	v_lshlrev_b32_e32 v29, 16, v74
	v_and_b32_e32 v33, 0xffff0000, v74
	v_mul_f32_e32 v29, v42, v29
	v_mul_f32_e32 v33, v43, v33
	v_pk_add_f32 v[40:41], v[82:83], v[50:51] op_sel_hi:[1,0]
	v_cvt_pk_bf16_f32 v42, v29, v33
	v_lshlrev_b32_e32 v29, 16, v75
	v_and_b32_e32 v33, 0xffff0000, v75
	v_mul_f32_e32 v29, v40, v29
	v_mul_f32_e32 v33, v41, v33
	v_cvt_pk_bf16_f32 v43, v29, v33
	global_store_dwordx2 v[38:39], v[42:43], off offset:96
	s_waitcnt vmcnt(13)
	v_pk_add_f32 v[42:43], v[60:61], v[100:101] op_sel_hi:[1,0]
	v_lshlrev_b32_e32 v29, 16, v92
	v_mul_f32_e32 v29, v42, v29
	v_and_b32_e32 v33, 0xffff0000, v92
	v_pk_add_f32 v[40:41], v[62:63], v[100:101] op_sel_hi:[1,0]
	v_mul_f32_e32 v33, v43, v33
	v_cvt_pk_bf16_f32 v42, v29, v33
	v_lshlrev_b32_e32 v29, 16, v93
	v_or_b32_e32 v38, 32, v32
	v_mul_f32_e32 v29, v40, v29
	v_and_b32_e32 v33, 0xffff0000, v93
	v_ashrrev_i32_e32 v39, 31, v38
	v_mul_f32_e32 v33, v41, v33
	v_cvt_pk_bf16_f32 v43, v29, v33
	v_pk_add_f32 v[20:21], v[20:21], v[100:101] op_sel_hi:[1,0]
	v_lshlrev_b32_e32 v29, 16, v94
	v_lshlrev_b64 v[38:39], 11, v[38:39]
	v_mul_f32_e32 v20, v20, v29
	v_and_b32_e32 v29, 0xffff0000, v94
	v_lshl_add_u64 v[38:39], v[104:105], 0, v[38:39]
	v_mul_f32_e32 v21, v21, v29
	global_store_dwordx2 v[38:39], v[42:43], off
	v_pk_add_f32 v[22:23], v[22:23], v[100:101] op_sel_hi:[1,0]
	v_cvt_pk_bf16_f32 v20, v20, v21
	v_lshlrev_b32_e32 v21, 16, v95
	v_mul_f32_e32 v21, v22, v21
	v_and_b32_e32 v22, 0xffff0000, v95
	v_mul_f32_e32 v22, v23, v22
	v_cvt_pk_bf16_f32 v21, v21, v22
	global_store_dwordx2 v[38:39], v[20:21], off offset:32
	v_pk_add_f32 v[16:17], v[16:17], v[100:101] op_sel_hi:[1,0]
	v_lshlrev_b32_e32 v20, 16, v96
	v_mul_f32_e32 v16, v16, v20
	v_and_b32_e32 v20, 0xffff0000, v96
	v_mul_f32_e32 v17, v17, v20
	v_pk_add_f32 v[18:19], v[18:19], v[100:101] op_sel_hi:[1,0]
	v_cvt_pk_bf16_f32 v16, v16, v17
	v_lshlrev_b32_e32 v17, 16, v97
	v_mul_f32_e32 v17, v18, v17
	v_and_b32_e32 v18, 0xffff0000, v97
	v_mul_f32_e32 v18, v19, v18
	v_cvt_pk_bf16_f32 v17, v17, v18
	v_pk_add_f32 v[18:19], v[24:25], v[100:101] op_sel_hi:[1,0]
	v_lshlrev_b32_e32 v20, 16, v98
	v_mul_f32_e32 v18, v18, v20
	v_and_b32_e32 v20, 0xffff0000, v98
	v_mul_f32_e32 v19, v19, v20
	global_store_dwordx2 v[38:39], v[16:17], off offset:64
	v_pk_add_f32 v[16:17], v[26:27], v[100:101] op_sel_hi:[1,0]
	v_cvt_pk_bf16_f32 v18, v18, v19
	v_lshlrev_b32_e32 v19, 16, v99
	v_mul_f32_e32 v16, v16, v19
	v_and_b32_e32 v19, 0xffff0000, v99
	v_mul_f32_e32 v17, v17, v19
	v_cvt_pk_bf16_f32 v19, v16, v17
	global_store_dwordx2 v[38:39], v[18:19], off offset:96
	s_waitcnt vmcnt(16)
	v_pk_add_f32 v[12:13], v[12:13], v[28:29] op_sel_hi:[1,0]
	s_waitcnt vmcnt(15)
	v_lshlrev_b32_e32 v18, 16, v102
	v_or_b32_e32 v16, 48, v32
	v_mul_f32_e32 v12, v12, v18
	v_and_b32_e32 v18, 0xffff0000, v102
	v_ashrrev_i32_e32 v17, 31, v16
	v_mul_f32_e32 v13, v13, v18
	v_lshlrev_b64 v[16:17], 11, v[16:17]
	v_pk_add_f32 v[14:15], v[14:15], v[28:29] op_sel_hi:[1,0]
	v_cvt_pk_bf16_f32 v12, v12, v13
	v_lshlrev_b32_e32 v13, 16, v103
	v_lshl_add_u64 v[16:17], v[104:105], 0, v[16:17]
	v_mul_f32_e32 v13, v14, v13
	v_and_b32_e32 v14, 0xffff0000, v103
	v_mul_f32_e32 v14, v15, v14
	v_cvt_pk_bf16_f32 v13, v13, v14
	global_store_dwordx2 v[16:17], v[12:13], off
	v_pk_add_f32 v[4:5], v[4:5], v[28:29] op_sel_hi:[1,0]
	s_waitcnt vmcnt(15)
	v_lshlrev_b32_e32 v12, 16, v36
	v_mul_f32_e32 v4, v4, v12
	v_and_b32_e32 v12, 0xffff0000, v36
	v_mul_f32_e32 v5, v5, v12
	v_pk_add_f32 v[6:7], v[6:7], v[28:29] op_sel_hi:[1,0]
	v_cvt_pk_bf16_f32 v4, v4, v5
	v_lshlrev_b32_e32 v5, 16, v37
	v_mul_f32_e32 v5, v6, v5
	v_and_b32_e32 v6, 0xffff0000, v37
	v_mul_f32_e32 v6, v7, v6
	v_cvt_pk_bf16_f32 v5, v5, v6
	global_store_dwordx2 v[16:17], v[4:5], off offset:32
	v_pk_add_f32 v[0:1], v[0:1], v[28:29] op_sel_hi:[1,0]
	s_waitcnt vmcnt(15)
	v_lshlrev_b32_e32 v4, 16, v34
	v_mul_f32_e32 v0, v0, v4
	v_and_b32_e32 v4, 0xffff0000, v34
	v_mul_f32_e32 v1, v1, v4
	v_pk_add_f32 v[2:3], v[2:3], v[28:29] op_sel_hi:[1,0]
	v_cvt_pk_bf16_f32 v0, v0, v1
	v_lshlrev_b32_e32 v1, 16, v35
	v_mul_f32_e32 v1, v2, v1
	v_and_b32_e32 v2, 0xffff0000, v35
	v_mul_f32_e32 v2, v3, v2
	v_cvt_pk_bf16_f32 v1, v1, v2
	v_pk_add_f32 v[2:3], v[8:9], v[28:29] op_sel_hi:[1,0]
	s_waitcnt vmcnt(14)
	v_lshlrev_b32_e32 v4, 16, v30
	v_mul_f32_e32 v2, v2, v4
	v_and_b32_e32 v4, 0xffff0000, v30
	v_mul_f32_e32 v3, v3, v4
	global_store_dwordx2 v[16:17], v[0:1], off offset:64
	v_pk_add_f32 v[0:1], v[10:11], v[28:29] op_sel_hi:[1,0]
	v_cvt_pk_bf16_f32 v2, v2, v3
	v_lshlrev_b32_e32 v3, 16, v31
	v_mul_f32_e32 v0, v0, v3
	v_and_b32_e32 v3, 0xffff0000, v31
	v_mul_f32_e32 v1, v1, v3
	v_cvt_pk_bf16_f32 v3, v0, v1
	global_store_dwordx2 v[16:17], v[2:3], off offset:96
	s_barrier
.LBB0_440:
	s_cmpk_lt_i32 s2, 0x100
	s_cbranch_scc1 .LBB0_437
	s_and_b32 s14, s2, 7
	s_lshl_b32 s14, s14, 5
	s_bfe_u32 s100, s2, 0x50003
	s_or_b32 s14, s14, s100
	s_and_b32 s100, s2, 0x300
	s_or_b32 s14, s14, s100
	s_lshl_b32 s14, s14, 5
	s_and_b32 s20, s14, 0x1fe0
	s_add_i32 s20, s20, -15
	v_add_u32_e32 v1, s20, v156
	s_movk_i32 s21, 0x2000
	s_add_i32 s11, s14, 0xffffe000
	v_cmp_gt_u32_e32 vcc, s21, v1
	s_and_b32 s14, s11, 0x2000
	s_and_b64 s[22:23], s[0:1], vcc
	v_mov_b32_e32 v0, 0
	v_mov_b32_e32 v4, 0
	v_mov_b32_e32 v5, 0
	v_mov_b32_e32 v6, 0
	v_mov_b32_e32 v7, 0
	s_and_saveexec_b64 s[34:35], s[22:23]
	s_cbranch_execz .LBB0_443
	v_or_b32_e32 v1, s14, v1
	v_lshlrev_b32_e32 v2, 10, v1
	v_mov_b32_e32 v3, v177
	v_lshl_add_u64 v[2:3], v[120:121], 0, v[2:3]
	global_load_dwordx4 v[4:7], v[2:3], off
